# prep phase rewritten: 8-lane head groups, rope pairs in-lane, LDS cos/sin table, 2 units of loads in flight
# speedup vs baseline: 1.0294x; 1.0128x over previous
; __device__ __forceinline__ bf16_t f2bf(float f) { return (bf16_t)(cvt_pk_bf16(f, 0.f) & 0xffffu); }
; __device__ __forceinline__ void prep_phase(const Ctx& X, const bf16_t* QKV, const float* qg, const float* kg, bf16_t* QP, bf16_t* KP, bf16_t* VT) {
;     bf16_t* vt = (bf16_t*)X.lds;
;     const float qgl = qg[X.lane], kgl = kg[X.lane];
;     const int f = X.lane & 31; const float invf = exp2f(-(float)(f & 15) * (13.287712379549449f / 16.0f));
;     for (int unit = X.bx; unit < MALL / 64; unit += X.G) {
;         const int R0 = unit * 64; const bool lat = R0 < MX; const int b = lat ? (R0 >> 12) : ((R0 - MX) >> 8); const int t0 = lat ? (R0 & 4095) : ((R0 - MX) & 255); const int kp0 = lat ? t0 : 4096 + t0;
;         __syncthreads();
;         for (int rr = 0; rr < 8; ++rr) { const int tl = X.wave * 8 + rr, R = R0 + tl, t = t0 + tl;
;             const bf16_t* rowp = QKV + (size_t)R * QKVW;
;             const float pos = (f < 16) ? (float)(t >> 6) : (float)(t & 63); const float ang = pos * invf; const float rev = __builtin_amdgcn_fractf(ang * 0.15915494309189535f); const float cs = __builtin_amdgcn_cosf(rev), sn = __builtin_amdgcn_sinf(rev);
;     ...
; #pragma unroll
;             for (int h = 0; h < 2; ++h) { const float x = bf2f(rowp[512 + h * 64 + X.lane]); float y = x * rsqrtf(wave_sum(x * x) * (1.0f / 64.0f) + 1e-6f) * kgl;
;                 if (lat) { const float pr = __shfl_xor(y, 32); y = X.lane < 32 ? (y * cs - pr * sn) : (pr * sn + y * cs); }
;                 KP[((size_t)(b * 2 + h) * KPL + kp0 + tl) * 64 + X.lane] = f2bf(y);
;                 vt[(h * 64 + X.lane) * 72 + tl] = rowp[640 + h * 64 + X.lane]; }
.LBB0_609:
	s_or_b64 exec, exec, s[0:1]
	s_add_u32 s26, s88, 0x10d00000
	s_addc_u32 s27, s89, 0
	s_add_u32 s24, s88, 0x17d00000
	s_addc_u32 s25, s89, 0
	v_mov_b32_e32 v6, v206
	s_waitcnt lgkmcnt(0)
	s_barrier
	v_readfirstlane_b32 s12, v206
	s_lshr_b32 s12, s12, 6
	v_and_b32_e32 v1, 63, v206
	s_cmpk_gt_i32 s2, 0x21f
	s_cbranch_scc1 .LBB0_624
	v_lshlrev_b32_e32 v20, 1, v206
	v_add_u32_e32 v21, 0, v20
	v_and_b32_e32 v22, 15, v21
	v_lshrrev_b32_e32 v23, 4, v21
	v_cvt_f32_u32_e32 v22, v22
	v_cvt_f32_u32_e32 v23, v23
	v_mul_f32_e32 v22, 0xbf549a78, v22
	v_exp_f32_e32 v22, v22
	s_nop 0
	v_mul_f32_e32 v22, v23, v22
	v_mul_f32_e32 v22, 0.15915494, v22
	v_fract_f32_e32 v22, v22
	v_cos_f32_e32 v24, v22
	v_sin_f32_e32 v25, v22
	v_lshlrev_b32_e32 v21, 2, v21
	ds_write_b32 v21, v24 offset:18432
	ds_write_b32 v21, v25 offset:22528
	v_add_u32_e32 v21, 1, v20
	v_and_b32_e32 v22, 15, v21
	v_lshrrev_b32_e32 v23, 4, v21
	v_cvt_f32_u32_e32 v22, v22
	v_cvt_f32_u32_e32 v23, v23
	v_mul_f32_e32 v22, 0xbf549a78, v22
	v_exp_f32_e32 v22, v22
	s_nop 0
	v_mul_f32_e32 v22, v23, v22
	v_mul_f32_e32 v22, 0.15915494, v22
	v_fract_f32_e32 v22, v22
	v_cos_f32_e32 v24, v22
	v_sin_f32_e32 v25, v22
	v_lshlrev_b32_e32 v21, 2, v21
	ds_write_b32 v21, v24 offset:18432
	ds_write_b32 v21, v25 offset:22528
	v_and_b32_e32 v20, 7, v1
	v_lshrrev_b32_e32 v21, 3, v1
	v_lshlrev_b32_e32 v22, 3, v20
	v_lshl_add_u32 v2, v21, 7, v22
	v_lshrrev_b32_e32 v23, 4, v1
	v_and_b32_e32 v24, 1, v21
	s_movk_i32 s0, 0x600
	v_mul_lo_u32 v25, v23, s0
	v_lshl_add_u32 v25, v24, 7, v25
	v_add_u32_e32 v25, v25, v22
	v_add_u32_e32 v3, 0x400, v25
	s_mov_b32 s0, 0x88000
	v_mul_lo_u32 v25, v24, s0
	v_lshl_add_u32 v25, v23, 7, v25
	v_add_u32_e32 v4, v25, v22
	v_lshrrev_b32_e32 v23, 5, v1
	v_and_b32_e32 v24, 31, v1
	s_movk_i32 s0, 0x600
	v_mul_lo_u32 v25, v23, s0
	v_lshl_add_u32 v25, v24, 3, v25
	v_add_u32_e32 v5, 0x500, v25
	s_movk_i32 s0, 0x240
	v_mul_lo_u32 v25, v24, s0
	v_lshl_add_u32 v25, v23, 1, v25
	s_lshl_b32 s0, s12, 4
	v_add_u32_e32 v6, s0, v25
	v_lshrrev_b32_e32 v23, 2, v206
	v_and_b32_e32 v24, 3, v206
	v_lshlrev_b32_e32 v24, 5, v24
	s_movk_i32 s0, 0x90
	v_mul_lo_u32 v25, v23, s0
	v_add_u32_e32 v7, v25, v24
	s_movk_i32 s0, 0x2200
	v_mul_lo_u32 v25, v23, s0
	v_add_u32_e32 v8, v25, v24
	v_and_b32_e32 v23, 3, v20
	v_lshlrev_b32_e32 v9, 4, v23
	v_cmp_gt_u32_e64 s[10:11], 4, v20
	v_mov_b32_e32 v10, 0x358637bd
	v_mov_b32_e32 v12, 0x3e38aa3b
	v_lshrrev_b32_e32 v15, 4, v1
	v_lshlrev_b32_e32 v63, 4, v20
	global_load_dwordx4 v[16:19], v63, s[58:59]
	global_load_dwordx4 v[20:23], v63, s[58:59] offset:128
	global_load_dwordx4 v[24:27], v63, s[60:61]
	global_load_dwordx4 v[28:31], v63, s[60:61] offset:128
	s_waitcnt vmcnt(0) lgkmcnt(0)
	s_barrier
	s_mov_b32 s13, s2
	s_mul_i32 s0, s90, 1
	s_add_u32 s21, s2, s0
	s_mul_i32 s0, s13, 0x18000
	s_mul_i32 s1, s12, 0x3000
	s_add_u32 s0, s0, s1
	s_add_u32 s4, s88, s0
	s_addc_u32 s5, s89, 0
	s_add_u32 s4, s4, 0x7500000
	s_addc_u32 s5, s5, 0
	s_add_u32 s6, s4, 0x1800
	s_addc_u32 s7, s5, 0
	global_load_dwordx2 v[104:105], v5, s[4:5]
	global_load_dwordx2 v[106:107], v5, s[4:5] offset:3072
	global_load_dwordx2 v[108:109], v5, s[6:7]
	global_load_dwordx2 v[110:111], v5, s[6:7] offset:3072
	global_load_dwordx2 v[96:97], v3, s[4:5]
	global_load_dwordx2 v[98:99], v3, s[4:5] offset:64
	global_load_dwordx2 v[100:101], v3, s[6:7]
	global_load_dwordx2 v[102:103], v3, s[6:7] offset:64
	global_load_dwordx2 v[64:65], v2, s[4:5]
	global_load_dwordx2 v[66:67], v2, s[4:5] offset:64
	global_load_dwordx2 v[68:69], v2, s[4:5] offset:1536
	global_load_dwordx2 v[70:71], v2, s[4:5] offset:1600
	s_add_u32 s4, s4, 0xc00
	s_addc_u32 s5, s5, 0
	global_load_dwordx2 v[72:73], v2, s[4:5]
	global_load_dwordx2 v[74:75], v2, s[4:5] offset:64
	global_load_dwordx2 v[76:77], v2, s[4:5] offset:1536
	global_load_dwordx2 v[78:79], v2, s[4:5] offset:1600
	s_add_u32 s4, s4, 0xc00
	s_addc_u32 s5, s5, 0
	global_load_dwordx2 v[80:81], v2, s[4:5]
	global_load_dwordx2 v[82:83], v2, s[4:5] offset:64
	global_load_dwordx2 v[84:85], v2, s[4:5] offset:1536
	global_load_dwordx2 v[86:87], v2, s[4:5] offset:1600
	s_add_u32 s4, s4, 0xc00
	s_addc_u32 s5, s5, 0
	global_load_dwordx2 v[88:89], v2, s[4:5]
	global_load_dwordx2 v[90:91], v2, s[4:5] offset:64
	global_load_dwordx2 v[92:93], v2, s[4:5] offset:1536
	global_load_dwordx2 v[94:95], v2, s[4:5] offset:1600
	s_mul_i32 s0, s21, 0x18000
	s_mul_i32 s1, s12, 0x3000
	s_add_u32 s0, s0, s1
	s_add_u32 s4, s88, s0
	s_addc_u32 s5, s89, 0
	s_add_u32 s4, s4, 0x7500000
	s_addc_u32 s5, s5, 0
	s_add_u32 s6, s4, 0x1800
	s_addc_u32 s7, s5, 0
	global_load_dwordx2 v[152:153], v5, s[4:5]
	global_load_dwordx2 v[154:155], v5, s[4:5] offset:3072
	global_load_dwordx2 v[156:157], v5, s[6:7]
	global_load_dwordx2 v[158:159], v5, s[6:7] offset:3072
	global_load_dwordx2 v[144:145], v3, s[4:5]
	global_load_dwordx2 v[146:147], v3, s[4:5] offset:64
	global_load_dwordx2 v[148:149], v3, s[6:7]
	global_load_dwordx2 v[150:151], v3, s[6:7] offset:64
	global_load_dwordx2 v[112:113], v2, s[4:5]
	global_load_dwordx2 v[114:115], v2, s[4:5] offset:64
	global_load_dwordx2 v[116:117], v2, s[4:5] offset:1536
	global_load_dwordx2 v[118:119], v2, s[4:5] offset:1600
	s_add_u32 s4, s4, 0xc00
	s_addc_u32 s5, s5, 0
	global_load_dwordx2 v[120:121], v2, s[4:5]
	global_load_dwordx2 v[122:123], v2, s[4:5] offset:64
	global_load_dwordx2 v[124:125], v2, s[4:5] offset:1536
	global_load_dwordx2 v[126:127], v2, s[4:5] offset:1600
	s_add_u32 s4, s4, 0xc00
	s_addc_u32 s5, s5, 0
	global_load_dwordx2 v[128:129], v2, s[4:5]
	global_load_dwordx2 v[130:131], v2, s[4:5] offset:64
	global_load_dwordx2 v[132:133], v2, s[4:5] offset:1536
	global_load_dwordx2 v[134:135], v2, s[4:5] offset:1600
	s_add_u32 s4, s4, 0xc00
	s_addc_u32 s5, s5, 0
	global_load_dwordx2 v[136:137], v2, s[4:5]
	global_load_dwordx2 v[138:139], v2, s[4:5] offset:64
	global_load_dwordx2 v[140:141], v2, s[4:5] offset:1536
	global_load_dwordx2 v[142:143], v2, s[4:5] offset:1600
	s_lshr_b32 s33, s13, 6
	s_and_b32 s35, s13, 63
	s_lshl_b32 s34, s35, 6
	v_mov_b32_e32 v14, s35
	s_mul_i32 s0, s33, 0x110000
	s_lshl_b32 s1, s12, 3
	s_add_u32 s1, s1, s34
	s_lshl_b32 s1, s1, 7
	s_add_u32 s0, s0, s1
	s_add_u32 s36, s88, s0
	s_addc_u32 s37, s89, 0
	s_add_u32 s36, s36, 0x17400000
	s_addc_u32 s37, s37, 0
	s_mul_i32 s0, s33, 0x110000
	s_lshl_b32 s1, s34, 1
	s_add_u32 s0, s0, s1
	s_add_u32 s38, s88, s0
	s_addc_u32 s39, s89, 0
	s_add_u32 s38, s38, 0x17d00000
	s_addc_u32 s39, s39, 0
	s_lshl_b32 s0, s13, 16
	s_lshl_b32 s1, s12, 13
	s_add_u32 s0, s0, s1
	s_add_u32 s30, s88, s0
	s_addc_u32 s31, s89, 0
	s_add_u32 s30, s30, 0x10d00000
	s_addc_u32 s31, s31, 0
	s_barrier
; __device__ __forceinline__ bf16_t f2bf(float f) { return (bf16_t)(cvt_pk_bf16(f, 0.f) & 0xffffu); }
; __device__ __forceinline__ void prep_phase(const Ctx& X, const bf16_t* QKV, const float* qg, const float* kg, bf16_t* QP, bf16_t* KP, bf16_t* VT) {
;     ...
;             for (int h = 0; h < 2; ++h) { const float x = bf2f(rowp[512 + h * 64 + X.lane]); float y = x * rsqrtf(wave_sum(x * x) * (1.0f / 64.0f) + 1e-6f) * kgl;
;                 if (lat) { const float pr = __shfl_xor(y, 32); y = X.lane < 32 ? (y * cs - pr * sn) : (pr * sn + y * cs); }
;                 KP[((size_t)(b * 2 + h) * KPL + kp0 + tl) * 64 + X.lane] = f2bf(y);
;                 vt[(h * 64 + X.lane) * 72 + tl] = rowp[640 + h * 64 + X.lane]; }
	s_waitcnt vmcnt(44)
	ds_write_b16 v6, v104 offset:0
	ds_write_b16_d16_hi v6, v104 offset:144
	ds_write_b16 v6, v105 offset:288
	ds_write_b16_d16_hi v6, v105 offset:432
	ds_write_b16 v6, v106 offset:4
	ds_write_b16_d16_hi v6, v106 offset:148
	ds_write_b16 v6, v107 offset:292
	ds_write_b16_d16_hi v6, v107 offset:436
	ds_write_b16 v6, v108 offset:8
	ds_write_b16_d16_hi v6, v108 offset:152
	ds_write_b16 v6, v109 offset:296
	ds_write_b16_d16_hi v6, v109 offset:440
	ds_write_b16 v6, v110 offset:12
	ds_write_b16_d16_hi v6, v110 offset:156
	ds_write_b16 v6, v111 offset:300
	ds_write_b16_d16_hi v6, v111 offset:444
	s_waitcnt vmcnt(42)
	s_lshl_b32 s0, s12, 3
	s_add_u32 s0, s0, 0
	v_add_u32_e32 v63, s0, v15
	v_cndmask_b32_e64 v63, v63, v14, s[10:11]
	v_lshl_add_u32 v62, v63, 6, v9
	ds_read_b128 v[50:53], v62 offset:18432
	ds_read_b128 v[54:57], v62 offset:22528
	v_lshlrev_b32_e32 v32, 16, v96
	v_and_b32_e32 v33, 0xffff0000, v96
	v_lshlrev_b32_e32 v34, 16, v97
	v_and_b32_e32 v35, 0xffff0000, v97
	v_lshlrev_b32_e32 v36, 16, v98
	v_and_b32_e32 v37, 0xffff0000, v98
	v_lshlrev_b32_e32 v38, 16, v99
	v_and_b32_e32 v39, 0xffff0000, v99
	v_pk_mul_f32 v[40:41], v[32:33], v[32:33]
	v_pk_fma_f32 v[40:41], v[34:35], v[34:35], v[40:41]
	v_pk_fma_f32 v[40:41], v[36:37], v[36:37], v[40:41]
	v_pk_fma_f32 v[40:41], v[38:39], v[38:39], v[40:41]
	v_add_f32_e32 v40, v40, v41
	s_nop 1
	v_add_f32_dpp v40, v40, v40 quad_perm:[1,0,3,2] row_mask:0xf bank_mask:0xf
	s_nop 1
	v_add_f32_dpp v40, v40, v40 quad_perm:[2,3,0,1] row_mask:0xf bank_mask:0xf
	s_nop 1
	v_add_f32_dpp v40, v40, v40 row_half_mirror row_mask:0xf bank_mask:0xf
	s_nop 1
	v_fmamk_f32 v40, v40, 0x3c800000, v10
	v_rsq_f32_e32 v40, v40
	s_nop 0
	v_pk_mul_f32 v[32:33], v[32:33], v[40:41] op_sel_hi:[1,0]
	v_pk_mul_f32 v[34:35], v[34:35], v[40:41] op_sel_hi:[1,0]
	v_pk_mul_f32 v[36:37], v[36:37], v[40:41] op_sel_hi:[1,0]
	v_pk_mul_f32 v[38:39], v[38:39], v[40:41] op_sel_hi:[1,0]
	v_pk_mul_f32 v[32:33], v[32:33], v[24:25]
	v_pk_mul_f32 v[34:35], v[34:35], v[26:27]
	v_pk_mul_f32 v[36:37], v[36:37], v[28:29]
	v_pk_mul_f32 v[38:39], v[38:39], v[30:31]
	s_waitcnt lgkmcnt(0)
	v_pk_mul_f32 v[42:43], v[36:37], v[54:55]
	v_pk_mul_f32 v[44:45], v[38:39], v[56:57]
	v_pk_mul_f32 v[46:47], v[32:33], v[54:55]
	v_pk_mul_f32 v[48:49], v[34:35], v[56:57]
	v_pk_fma_f32 v[32:33], v[32:33], v[50:51], v[42:43] neg_lo:[0,0,1] neg_hi:[0,0,1]
	v_pk_fma_f32 v[34:35], v[34:35], v[52:53], v[44:45] neg_lo:[0,0,1] neg_hi:[0,0,1]
	v_pk_fma_f32 v[36:37], v[36:37], v[50:51], v[46:47]
	v_pk_fma_f32 v[38:39], v[38:39], v[52:53], v[48:49]
	v_cvt_pk_bf16_f32 v58, v32, v33
	v_cvt_pk_bf16_f32 v59, v34, v35
	v_cvt_pk_bf16_f32 v60, v36, v37
	v_cvt_pk_bf16_f32 v61, v38, v39
	global_store_dwordx2 v4, v[58:59], s[36:37]
	global_store_dwordx2 v4, v[60:61], s[36:37] offset:64
	s_waitcnt vmcnt(42)
	s_lshl_b32 s0, s12, 3
	s_add_u32 s0, s0, 4
	v_add_u32_e32 v63, s0, v15
	v_cndmask_b32_e64 v63, v63, v14, s[10:11]
	v_lshl_add_u32 v62, v63, 6, v9
	ds_read_b128 v[50:53], v62 offset:18432
	ds_read_b128 v[54:57], v62 offset:22528
	v_lshlrev_b32_e32 v32, 16, v100
	v_and_b32_e32 v33, 0xffff0000, v100
	v_lshlrev_b32_e32 v34, 16, v101
	v_and_b32_e32 v35, 0xffff0000, v101
	v_lshlrev_b32_e32 v36, 16, v102
	v_and_b32_e32 v37, 0xffff0000, v102
	v_lshlrev_b32_e32 v38, 16, v103
	v_and_b32_e32 v39, 0xffff0000, v103
	v_pk_mul_f32 v[40:41], v[32:33], v[32:33]
	v_pk_fma_f32 v[40:41], v[34:35], v[34:35], v[40:41]
	v_pk_fma_f32 v[40:41], v[36:37], v[36:37], v[40:41]
	v_pk_fma_f32 v[40:41], v[38:39], v[38:39], v[40:41]
	v_add_f32_e32 v40, v40, v41
	s_nop 1
	v_add_f32_dpp v40, v40, v40 quad_perm:[1,0,3,2] row_mask:0xf bank_mask:0xf
	s_nop 1
	v_add_f32_dpp v40, v40, v40 quad_perm:[2,3,0,1] row_mask:0xf bank_mask:0xf
	s_nop 1
	v_add_f32_dpp v40, v40, v40 row_half_mirror row_mask:0xf bank_mask:0xf
	s_nop 1
	v_fmamk_f32 v40, v40, 0x3c800000, v10
	v_rsq_f32_e32 v40, v40
	s_nop 0
	v_pk_mul_f32 v[32:33], v[32:33], v[40:41] op_sel_hi:[1,0]
	v_pk_mul_f32 v[34:35], v[34:35], v[40:41] op_sel_hi:[1,0]
	v_pk_mul_f32 v[36:37], v[36:37], v[40:41] op_sel_hi:[1,0]
	v_pk_mul_f32 v[38:39], v[38:39], v[40:41] op_sel_hi:[1,0]
	v_pk_mul_f32 v[32:33], v[32:33], v[24:25]
	v_pk_mul_f32 v[34:35], v[34:35], v[26:27]
	v_pk_mul_f32 v[36:37], v[36:37], v[28:29]
	v_pk_mul_f32 v[38:39], v[38:39], v[30:31]
	s_waitcnt lgkmcnt(0)
	v_pk_mul_f32 v[42:43], v[36:37], v[54:55]
	v_pk_mul_f32 v[44:45], v[38:39], v[56:57]
	v_pk_mul_f32 v[46:47], v[32:33], v[54:55]
	v_pk_mul_f32 v[48:49], v[34:35], v[56:57]
	v_pk_fma_f32 v[32:33], v[32:33], v[50:51], v[42:43] neg_lo:[0,0,1] neg_hi:[0,0,1]
	v_pk_fma_f32 v[34:35], v[34:35], v[52:53], v[44:45] neg_lo:[0,0,1] neg_hi:[0,0,1]
	v_pk_fma_f32 v[36:37], v[36:37], v[50:51], v[46:47]
	v_pk_fma_f32 v[38:39], v[38:39], v[52:53], v[48:49]
	v_cvt_pk_bf16_f32 v58, v32, v33
	v_cvt_pk_bf16_f32 v59, v34, v35
	v_cvt_pk_bf16_f32 v60, v36, v37
	v_cvt_pk_bf16_f32 v61, v38, v39
	global_store_dwordx2 v4, v[58:59], s[36:37] offset:512
	global_store_dwordx2 v4, v[60:61], s[36:37] offset:576
	s_waitcnt vmcnt(42)
; __device__ __forceinline__ bf16_t f2bf(float f) { return (bf16_t)(cvt_pk_bf16(f, 0.f) & 0xffffu); }
; __device__ __forceinline__ void prep_phase(const Ctx& X, const bf16_t* QKV, const float* qg, const float* kg, bf16_t* QP, bf16_t* KP, bf16_t* VT) {
;     ...
;                 for (int h = 0; h < 8; ++h) { const float x = bf2f(rowp[h * 64 + X.lane]); const float y = x * rsqrtf(wave_sum(x * x) * (1.0f / 64.0f) + 1e-6f) * qgl; const float pr = __shfl_xor(y, 32);
;                     const float o = X.lane < 32 ? (y * cs - pr * sn) : (pr * sn + y * cs); QP[((size_t)R * 8 + h) * 64 + X.lane] = f2bf(o * (0.125f * LOG2E)); } }
	s_lshl_b32 s0, s12, 3
	v_mov_b32_e32 v63, s0
	v_cndmask_b32_e64 v63, v63, v14, s[10:11]
	v_lshl_add_u32 v62, v63, 6, v9
	ds_read_b128 v[50:53], v62 offset:18432
	ds_read_b128 v[54:57], v62 offset:22528
	v_lshlrev_b32_e32 v32, 16, v64
	v_and_b32_e32 v33, 0xffff0000, v64
	v_lshlrev_b32_e32 v34, 16, v65
	v_and_b32_e32 v35, 0xffff0000, v65
	v_lshlrev_b32_e32 v36, 16, v66
	v_and_b32_e32 v37, 0xffff0000, v66
	v_lshlrev_b32_e32 v38, 16, v67
	v_and_b32_e32 v39, 0xffff0000, v67
	v_pk_mul_f32 v[40:41], v[32:33], v[32:33]
	v_pk_fma_f32 v[40:41], v[34:35], v[34:35], v[40:41]
	v_pk_fma_f32 v[40:41], v[36:37], v[36:37], v[40:41]
	v_pk_fma_f32 v[40:41], v[38:39], v[38:39], v[40:41]
	v_add_f32_e32 v40, v40, v41
	s_nop 1
	v_add_f32_dpp v40, v40, v40 quad_perm:[1,0,3,2] row_mask:0xf bank_mask:0xf
	s_nop 1
	v_add_f32_dpp v40, v40, v40 quad_perm:[2,3,0,1] row_mask:0xf bank_mask:0xf
	s_nop 1
	v_add_f32_dpp v40, v40, v40 row_half_mirror row_mask:0xf bank_mask:0xf
	s_nop 1
	v_fmamk_f32 v40, v40, 0x3c800000, v10
	v_rsq_f32_e32 v40, v40
	s_nop 0
	v_pk_mul_f32 v[32:33], v[32:33], v[40:41] op_sel_hi:[1,0]
	v_pk_mul_f32 v[34:35], v[34:35], v[40:41] op_sel_hi:[1,0]
	v_pk_mul_f32 v[36:37], v[36:37], v[40:41] op_sel_hi:[1,0]
	v_pk_mul_f32 v[38:39], v[38:39], v[40:41] op_sel_hi:[1,0]
	v_pk_mul_f32 v[32:33], v[32:33], v[16:17]
	v_pk_mul_f32 v[34:35], v[34:35], v[18:19]
	v_pk_mul_f32 v[36:37], v[36:37], v[20:21]
	v_pk_mul_f32 v[38:39], v[38:39], v[22:23]
	s_waitcnt lgkmcnt(0)
	v_pk_mul_f32 v[42:43], v[36:37], v[54:55]
	v_pk_mul_f32 v[44:45], v[38:39], v[56:57]
	v_pk_mul_f32 v[46:47], v[32:33], v[54:55]
	v_pk_mul_f32 v[48:49], v[34:35], v[56:57]
	v_pk_fma_f32 v[32:33], v[32:33], v[50:51], v[42:43] neg_lo:[0,0,1] neg_hi:[0,0,1]
	v_pk_fma_f32 v[34:35], v[34:35], v[52:53], v[44:45] neg_lo:[0,0,1] neg_hi:[0,0,1]
	v_pk_fma_f32 v[36:37], v[36:37], v[50:51], v[46:47]
	v_pk_fma_f32 v[38:39], v[38:39], v[52:53], v[48:49]
	v_pk_mul_f32 v[32:33], v[32:33], v[12:13] op_sel_hi:[1,0]
	v_pk_mul_f32 v[34:35], v[34:35], v[12:13] op_sel_hi:[1,0]
	v_pk_mul_f32 v[36:37], v[36:37], v[12:13] op_sel_hi:[1,0]
	v_pk_mul_f32 v[38:39], v[38:39], v[12:13] op_sel_hi:[1,0]
	v_cvt_pk_bf16_f32 v58, v32, v33
	v_cvt_pk_bf16_f32 v59, v34, v35
	v_cvt_pk_bf16_f32 v60, v36, v37
	v_cvt_pk_bf16_f32 v61, v38, v39
	global_store_dwordx2 v2, v[58:59], s[30:31]
	global_store_dwordx2 v2, v[60:61], s[30:31] offset:64
	s_waitcnt vmcnt(42)
	s_lshl_b32 s0, s12, 3
	s_add_u32 s0, s0, 1
	v_mov_b32_e32 v63, s0
	v_cndmask_b32_e64 v63, v63, v14, s[10:11]
	v_lshl_add_u32 v62, v63, 6, v9
	ds_read_b128 v[50:53], v62 offset:18432
	ds_read_b128 v[54:57], v62 offset:22528
	v_lshlrev_b32_e32 v32, 16, v68
	v_and_b32_e32 v33, 0xffff0000, v68
	v_lshlrev_b32_e32 v34, 16, v69
	v_and_b32_e32 v35, 0xffff0000, v69
	v_lshlrev_b32_e32 v36, 16, v70
	v_and_b32_e32 v37, 0xffff0000, v70
	v_lshlrev_b32_e32 v38, 16, v71
	v_and_b32_e32 v39, 0xffff0000, v71
	v_pk_mul_f32 v[40:41], v[32:33], v[32:33]
	v_pk_fma_f32 v[40:41], v[34:35], v[34:35], v[40:41]
	v_pk_fma_f32 v[40:41], v[36:37], v[36:37], v[40:41]
	v_pk_fma_f32 v[40:41], v[38:39], v[38:39], v[40:41]
	v_add_f32_e32 v40, v40, v41
	s_nop 1
	v_add_f32_dpp v40, v40, v40 quad_perm:[1,0,3,2] row_mask:0xf bank_mask:0xf
	s_nop 1
	v_add_f32_dpp v40, v40, v40 quad_perm:[2,3,0,1] row_mask:0xf bank_mask:0xf
	s_nop 1
	v_add_f32_dpp v40, v40, v40 row_half_mirror row_mask:0xf bank_mask:0xf
	s_nop 1
	v_fmamk_f32 v40, v40, 0x3c800000, v10
	v_rsq_f32_e32 v40, v40
	s_nop 0
	v_pk_mul_f32 v[32:33], v[32:33], v[40:41] op_sel_hi:[1,0]
	v_pk_mul_f32 v[34:35], v[34:35], v[40:41] op_sel_hi:[1,0]
	v_pk_mul_f32 v[36:37], v[36:37], v[40:41] op_sel_hi:[1,0]
	v_pk_mul_f32 v[38:39], v[38:39], v[40:41] op_sel_hi:[1,0]
	v_pk_mul_f32 v[32:33], v[32:33], v[16:17]
	v_pk_mul_f32 v[34:35], v[34:35], v[18:19]
	v_pk_mul_f32 v[36:37], v[36:37], v[20:21]
	v_pk_mul_f32 v[38:39], v[38:39], v[22:23]
	s_waitcnt lgkmcnt(0)
	v_pk_mul_f32 v[42:43], v[36:37], v[54:55]
	v_pk_mul_f32 v[44:45], v[38:39], v[56:57]
	v_pk_mul_f32 v[46:47], v[32:33], v[54:55]
	v_pk_mul_f32 v[48:49], v[34:35], v[56:57]
	v_pk_fma_f32 v[32:33], v[32:33], v[50:51], v[42:43] neg_lo:[0,0,1] neg_hi:[0,0,1]
	v_pk_fma_f32 v[34:35], v[34:35], v[52:53], v[44:45] neg_lo:[0,0,1] neg_hi:[0,0,1]
	v_pk_fma_f32 v[36:37], v[36:37], v[50:51], v[46:47]
	v_pk_fma_f32 v[38:39], v[38:39], v[52:53], v[48:49]
	v_pk_mul_f32 v[32:33], v[32:33], v[12:13] op_sel_hi:[1,0]
	v_pk_mul_f32 v[34:35], v[34:35], v[12:13] op_sel_hi:[1,0]
	v_pk_mul_f32 v[36:37], v[36:37], v[12:13] op_sel_hi:[1,0]
	v_pk_mul_f32 v[38:39], v[38:39], v[12:13] op_sel_hi:[1,0]
	v_cvt_pk_bf16_f32 v58, v32, v33
	v_cvt_pk_bf16_f32 v59, v34, v35
	v_cvt_pk_bf16_f32 v60, v36, v37
	v_cvt_pk_bf16_f32 v61, v38, v39
	global_store_dwordx2 v2, v[58:59], s[30:31] offset:1024
	global_store_dwordx2 v2, v[60:61], s[30:31] offset:1088
	s_waitcnt vmcnt(42)
	s_lshl_b32 s0, s12, 3
	s_add_u32 s0, s0, 2
	v_mov_b32_e32 v63, s0
	v_cndmask_b32_e64 v63, v63, v14, s[10:11]
	v_lshl_add_u32 v62, v63, 6, v9
	ds_read_b128 v[50:53], v62 offset:18432
	ds_read_b128 v[54:57], v62 offset:22528
	v_lshlrev_b32_e32 v32, 16, v72
	v_and_b32_e32 v33, 0xffff0000, v72
	v_lshlrev_b32_e32 v34, 16, v73
	v_and_b32_e32 v35, 0xffff0000, v73
	v_lshlrev_b32_e32 v36, 16, v74
	v_and_b32_e32 v37, 0xffff0000, v74
	v_lshlrev_b32_e32 v38, 16, v75
	v_and_b32_e32 v39, 0xffff0000, v75
	v_pk_mul_f32 v[40:41], v[32:33], v[32:33]
	v_pk_fma_f32 v[40:41], v[34:35], v[34:35], v[40:41]
	v_pk_fma_f32 v[40:41], v[36:37], v[36:37], v[40:41]
	v_pk_fma_f32 v[40:41], v[38:39], v[38:39], v[40:41]
	v_add_f32_e32 v40, v40, v41
	s_nop 1
	v_add_f32_dpp v40, v40, v40 quad_perm:[1,0,3,2] row_mask:0xf bank_mask:0xf
	s_nop 1
	v_add_f32_dpp v40, v40, v40 quad_perm:[2,3,0,1] row_mask:0xf bank_mask:0xf
	s_nop 1
	v_add_f32_dpp v40, v40, v40 row_half_mirror row_mask:0xf bank_mask:0xf
	s_nop 1
	v_fmamk_f32 v40, v40, 0x3c800000, v10
	v_rsq_f32_e32 v40, v40
	s_nop 0
	v_pk_mul_f32 v[32:33], v[32:33], v[40:41] op_sel_hi:[1,0]
	v_pk_mul_f32 v[34:35], v[34:35], v[40:41] op_sel_hi:[1,0]
	v_pk_mul_f32 v[36:37], v[36:37], v[40:41] op_sel_hi:[1,0]
	v_pk_mul_f32 v[38:39], v[38:39], v[40:41] op_sel_hi:[1,0]
	v_pk_mul_f32 v[32:33], v[32:33], v[16:17]
	v_pk_mul_f32 v[34:35], v[34:35], v[18:19]
	v_pk_mul_f32 v[36:37], v[36:37], v[20:21]
	v_pk_mul_f32 v[38:39], v[38:39], v[22:23]
	s_waitcnt lgkmcnt(0)
; __device__ __forceinline__ bf16_t f2bf(float f) { return (bf16_t)(cvt_pk_bf16(f, 0.f) & 0xffffu); }
; __device__ __forceinline__ void prep_phase(const Ctx& X, const bf16_t* QKV, const float* qg, const float* kg, bf16_t* QP, bf16_t* KP, bf16_t* VT) {
;     ...
;                 for (int h = 0; h < 8; ++h) { const float x = bf2f(rowp[h * 64 + X.lane]); const float y = x * rsqrtf(wave_sum(x * x) * (1.0f / 64.0f) + 1e-6f) * qgl; const float pr = __shfl_xor(y, 32);
;                     const float o = X.lane < 32 ? (y * cs - pr * sn) : (pr * sn + y * cs); QP[((size_t)R * 8 + h) * 64 + X.lane] = f2bf(o * (0.125f * LOG2E)); } }
	v_pk_mul_f32 v[42:43], v[36:37], v[54:55]
	v_pk_mul_f32 v[44:45], v[38:39], v[56:57]
	v_pk_mul_f32 v[46:47], v[32:33], v[54:55]
	v_pk_mul_f32 v[48:49], v[34:35], v[56:57]
	v_pk_fma_f32 v[32:33], v[32:33], v[50:51], v[42:43] neg_lo:[0,0,1] neg_hi:[0,0,1]
	v_pk_fma_f32 v[34:35], v[34:35], v[52:53], v[44:45] neg_lo:[0,0,1] neg_hi:[0,0,1]
	v_pk_fma_f32 v[36:37], v[36:37], v[50:51], v[46:47]
	v_pk_fma_f32 v[38:39], v[38:39], v[52:53], v[48:49]
	v_pk_mul_f32 v[32:33], v[32:33], v[12:13] op_sel_hi:[1,0]
	v_pk_mul_f32 v[34:35], v[34:35], v[12:13] op_sel_hi:[1,0]
	v_pk_mul_f32 v[36:37], v[36:37], v[12:13] op_sel_hi:[1,0]
	v_pk_mul_f32 v[38:39], v[38:39], v[12:13] op_sel_hi:[1,0]
	v_cvt_pk_bf16_f32 v58, v32, v33
	v_cvt_pk_bf16_f32 v59, v34, v35
	v_cvt_pk_bf16_f32 v60, v36, v37
	v_cvt_pk_bf16_f32 v61, v38, v39
	global_store_dwordx2 v2, v[58:59], s[30:31] offset:2048
	global_store_dwordx2 v2, v[60:61], s[30:31] offset:2112
	s_waitcnt vmcnt(42)
	s_lshl_b32 s0, s12, 3
	s_add_u32 s0, s0, 3
	v_mov_b32_e32 v63, s0
	v_cndmask_b32_e64 v63, v63, v14, s[10:11]
	v_lshl_add_u32 v62, v63, 6, v9
	ds_read_b128 v[50:53], v62 offset:18432
	ds_read_b128 v[54:57], v62 offset:22528
	v_lshlrev_b32_e32 v32, 16, v76
	v_and_b32_e32 v33, 0xffff0000, v76
	v_lshlrev_b32_e32 v34, 16, v77
	v_and_b32_e32 v35, 0xffff0000, v77
	v_lshlrev_b32_e32 v36, 16, v78
	v_and_b32_e32 v37, 0xffff0000, v78
	v_lshlrev_b32_e32 v38, 16, v79
	v_and_b32_e32 v39, 0xffff0000, v79
	v_pk_mul_f32 v[40:41], v[32:33], v[32:33]
	v_pk_fma_f32 v[40:41], v[34:35], v[34:35], v[40:41]
	v_pk_fma_f32 v[40:41], v[36:37], v[36:37], v[40:41]
	v_pk_fma_f32 v[40:41], v[38:39], v[38:39], v[40:41]
	v_add_f32_e32 v40, v40, v41
	s_nop 1
	v_add_f32_dpp v40, v40, v40 quad_perm:[1,0,3,2] row_mask:0xf bank_mask:0xf
	s_nop 1
	v_add_f32_dpp v40, v40, v40 quad_perm:[2,3,0,1] row_mask:0xf bank_mask:0xf
	s_nop 1
	v_add_f32_dpp v40, v40, v40 row_half_mirror row_mask:0xf bank_mask:0xf
	s_nop 1
	v_fmamk_f32 v40, v40, 0x3c800000, v10
	v_rsq_f32_e32 v40, v40
	s_nop 0
	v_pk_mul_f32 v[32:33], v[32:33], v[40:41] op_sel_hi:[1,0]
	v_pk_mul_f32 v[34:35], v[34:35], v[40:41] op_sel_hi:[1,0]
	v_pk_mul_f32 v[36:37], v[36:37], v[40:41] op_sel_hi:[1,0]
	v_pk_mul_f32 v[38:39], v[38:39], v[40:41] op_sel_hi:[1,0]
	v_pk_mul_f32 v[32:33], v[32:33], v[16:17]
	v_pk_mul_f32 v[34:35], v[34:35], v[18:19]
	v_pk_mul_f32 v[36:37], v[36:37], v[20:21]
	v_pk_mul_f32 v[38:39], v[38:39], v[22:23]
	s_waitcnt lgkmcnt(0)
	v_pk_mul_f32 v[42:43], v[36:37], v[54:55]
	v_pk_mul_f32 v[44:45], v[38:39], v[56:57]
	v_pk_mul_f32 v[46:47], v[32:33], v[54:55]
	v_pk_mul_f32 v[48:49], v[34:35], v[56:57]
	v_pk_fma_f32 v[32:33], v[32:33], v[50:51], v[42:43] neg_lo:[0,0,1] neg_hi:[0,0,1]
	v_pk_fma_f32 v[34:35], v[34:35], v[52:53], v[44:45] neg_lo:[0,0,1] neg_hi:[0,0,1]
	v_pk_fma_f32 v[36:37], v[36:37], v[50:51], v[46:47]
	v_pk_fma_f32 v[38:39], v[38:39], v[52:53], v[48:49]
	v_pk_mul_f32 v[32:33], v[32:33], v[12:13] op_sel_hi:[1,0]
	v_pk_mul_f32 v[34:35], v[34:35], v[12:13] op_sel_hi:[1,0]
	v_pk_mul_f32 v[36:37], v[36:37], v[12:13] op_sel_hi:[1,0]
	v_pk_mul_f32 v[38:39], v[38:39], v[12:13] op_sel_hi:[1,0]
	v_cvt_pk_bf16_f32 v58, v32, v33
	v_cvt_pk_bf16_f32 v59, v34, v35
	v_cvt_pk_bf16_f32 v60, v36, v37
	v_cvt_pk_bf16_f32 v61, v38, v39
	global_store_dwordx2 v2, v[58:59], s[30:31] offset:3072
	global_store_dwordx2 v2, v[60:61], s[30:31] offset:3136
	s_waitcnt vmcnt(42)
	s_lshl_b32 s0, s12, 3
	s_add_u32 s0, s0, 4
	v_mov_b32_e32 v63, s0
	v_cndmask_b32_e64 v63, v63, v14, s[10:11]
	v_lshl_add_u32 v62, v63, 6, v9
	ds_read_b128 v[50:53], v62 offset:18432
	ds_read_b128 v[54:57], v62 offset:22528
	v_lshlrev_b32_e32 v32, 16, v80
	v_and_b32_e32 v33, 0xffff0000, v80
	v_lshlrev_b32_e32 v34, 16, v81
	v_and_b32_e32 v35, 0xffff0000, v81
	v_lshlrev_b32_e32 v36, 16, v82
	v_and_b32_e32 v37, 0xffff0000, v82
	v_lshlrev_b32_e32 v38, 16, v83
	v_and_b32_e32 v39, 0xffff0000, v83
	v_pk_mul_f32 v[40:41], v[32:33], v[32:33]
	v_pk_fma_f32 v[40:41], v[34:35], v[34:35], v[40:41]
	v_pk_fma_f32 v[40:41], v[36:37], v[36:37], v[40:41]
	v_pk_fma_f32 v[40:41], v[38:39], v[38:39], v[40:41]
	v_add_f32_e32 v40, v40, v41
	s_nop 1
	v_add_f32_dpp v40, v40, v40 quad_perm:[1,0,3,2] row_mask:0xf bank_mask:0xf
	s_nop 1
	v_add_f32_dpp v40, v40, v40 quad_perm:[2,3,0,1] row_mask:0xf bank_mask:0xf
	s_nop 1
	v_add_f32_dpp v40, v40, v40 row_half_mirror row_mask:0xf bank_mask:0xf
	s_nop 1
	v_fmamk_f32 v40, v40, 0x3c800000, v10
	v_rsq_f32_e32 v40, v40
	s_nop 0
	v_pk_mul_f32 v[32:33], v[32:33], v[40:41] op_sel_hi:[1,0]
	v_pk_mul_f32 v[34:35], v[34:35], v[40:41] op_sel_hi:[1,0]
	v_pk_mul_f32 v[36:37], v[36:37], v[40:41] op_sel_hi:[1,0]
	v_pk_mul_f32 v[38:39], v[38:39], v[40:41] op_sel_hi:[1,0]
	v_pk_mul_f32 v[32:33], v[32:33], v[16:17]
	v_pk_mul_f32 v[34:35], v[34:35], v[18:19]
	v_pk_mul_f32 v[36:37], v[36:37], v[20:21]
	v_pk_mul_f32 v[38:39], v[38:39], v[22:23]
	s_waitcnt lgkmcnt(0)
	v_pk_mul_f32 v[42:43], v[36:37], v[54:55]
	v_pk_mul_f32 v[44:45], v[38:39], v[56:57]
	v_pk_mul_f32 v[46:47], v[32:33], v[54:55]
	v_pk_mul_f32 v[48:49], v[34:35], v[56:57]
	v_pk_fma_f32 v[32:33], v[32:33], v[50:51], v[42:43] neg_lo:[0,0,1] neg_hi:[0,0,1]
	v_pk_fma_f32 v[34:35], v[34:35], v[52:53], v[44:45] neg_lo:[0,0,1] neg_hi:[0,0,1]
	v_pk_fma_f32 v[36:37], v[36:37], v[50:51], v[46:47]
	v_pk_fma_f32 v[38:39], v[38:39], v[52:53], v[48:49]
	v_pk_mul_f32 v[32:33], v[32:33], v[12:13] op_sel_hi:[1,0]
	v_pk_mul_f32 v[34:35], v[34:35], v[12:13] op_sel_hi:[1,0]
	v_pk_mul_f32 v[36:37], v[36:37], v[12:13] op_sel_hi:[1,0]
	v_pk_mul_f32 v[38:39], v[38:39], v[12:13] op_sel_hi:[1,0]
	v_cvt_pk_bf16_f32 v58, v32, v33
	v_cvt_pk_bf16_f32 v59, v34, v35
	v_cvt_pk_bf16_f32 v60, v36, v37
	v_cvt_pk_bf16_f32 v61, v38, v39
	s_add_u32 s30, s30, 0x1000
	s_addc_u32 s31, s31, 0
	global_store_dwordx2 v2, v[58:59], s[30:31]
	global_store_dwordx2 v2, v[60:61], s[30:31] offset:64
	s_waitcnt vmcnt(42)
; __device__ __forceinline__ bf16_t f2bf(float f) { return (bf16_t)(cvt_pk_bf16(f, 0.f) & 0xffffu); }
; __device__ __forceinline__ void prep_phase(const Ctx& X, const bf16_t* QKV, const float* qg, const float* kg, bf16_t* QP, bf16_t* KP, bf16_t* VT) {
;     ...
;                 for (int h = 0; h < 8; ++h) { const float x = bf2f(rowp[h * 64 + X.lane]); const float y = x * rsqrtf(wave_sum(x * x) * (1.0f / 64.0f) + 1e-6f) * qgl; const float pr = __shfl_xor(y, 32);
;                     const float o = X.lane < 32 ? (y * cs - pr * sn) : (pr * sn + y * cs); QP[((size_t)R * 8 + h) * 64 + X.lane] = f2bf(o * (0.125f * LOG2E)); } }
	s_lshl_b32 s0, s12, 3
	s_add_u32 s0, s0, 5
	v_mov_b32_e32 v63, s0
	v_cndmask_b32_e64 v63, v63, v14, s[10:11]
	v_lshl_add_u32 v62, v63, 6, v9
	ds_read_b128 v[50:53], v62 offset:18432
	ds_read_b128 v[54:57], v62 offset:22528
	v_lshlrev_b32_e32 v32, 16, v84
	v_and_b32_e32 v33, 0xffff0000, v84
	v_lshlrev_b32_e32 v34, 16, v85
	v_and_b32_e32 v35, 0xffff0000, v85
	v_lshlrev_b32_e32 v36, 16, v86
	v_and_b32_e32 v37, 0xffff0000, v86
	v_lshlrev_b32_e32 v38, 16, v87
	v_and_b32_e32 v39, 0xffff0000, v87
	v_pk_mul_f32 v[40:41], v[32:33], v[32:33]
	v_pk_fma_f32 v[40:41], v[34:35], v[34:35], v[40:41]
	v_pk_fma_f32 v[40:41], v[36:37], v[36:37], v[40:41]
	v_pk_fma_f32 v[40:41], v[38:39], v[38:39], v[40:41]
	v_add_f32_e32 v40, v40, v41
	s_nop 1
	v_add_f32_dpp v40, v40, v40 quad_perm:[1,0,3,2] row_mask:0xf bank_mask:0xf
	s_nop 1
	v_add_f32_dpp v40, v40, v40 quad_perm:[2,3,0,1] row_mask:0xf bank_mask:0xf
	s_nop 1
	v_add_f32_dpp v40, v40, v40 row_half_mirror row_mask:0xf bank_mask:0xf
	s_nop 1
	v_fmamk_f32 v40, v40, 0x3c800000, v10
	v_rsq_f32_e32 v40, v40
	s_nop 0
	v_pk_mul_f32 v[32:33], v[32:33], v[40:41] op_sel_hi:[1,0]
	v_pk_mul_f32 v[34:35], v[34:35], v[40:41] op_sel_hi:[1,0]
	v_pk_mul_f32 v[36:37], v[36:37], v[40:41] op_sel_hi:[1,0]
	v_pk_mul_f32 v[38:39], v[38:39], v[40:41] op_sel_hi:[1,0]
	v_pk_mul_f32 v[32:33], v[32:33], v[16:17]
	v_pk_mul_f32 v[34:35], v[34:35], v[18:19]
	v_pk_mul_f32 v[36:37], v[36:37], v[20:21]
	v_pk_mul_f32 v[38:39], v[38:39], v[22:23]
	s_waitcnt lgkmcnt(0)
	v_pk_mul_f32 v[42:43], v[36:37], v[54:55]
	v_pk_mul_f32 v[44:45], v[38:39], v[56:57]
	v_pk_mul_f32 v[46:47], v[32:33], v[54:55]
	v_pk_mul_f32 v[48:49], v[34:35], v[56:57]
	v_pk_fma_f32 v[32:33], v[32:33], v[50:51], v[42:43] neg_lo:[0,0,1] neg_hi:[0,0,1]
	v_pk_fma_f32 v[34:35], v[34:35], v[52:53], v[44:45] neg_lo:[0,0,1] neg_hi:[0,0,1]
	v_pk_fma_f32 v[36:37], v[36:37], v[50:51], v[46:47]
	v_pk_fma_f32 v[38:39], v[38:39], v[52:53], v[48:49]
	v_pk_mul_f32 v[32:33], v[32:33], v[12:13] op_sel_hi:[1,0]
	v_pk_mul_f32 v[34:35], v[34:35], v[12:13] op_sel_hi:[1,0]
	v_pk_mul_f32 v[36:37], v[36:37], v[12:13] op_sel_hi:[1,0]
	v_pk_mul_f32 v[38:39], v[38:39], v[12:13] op_sel_hi:[1,0]
	v_cvt_pk_bf16_f32 v58, v32, v33
	v_cvt_pk_bf16_f32 v59, v34, v35
	v_cvt_pk_bf16_f32 v60, v36, v37
	v_cvt_pk_bf16_f32 v61, v38, v39
	global_store_dwordx2 v2, v[58:59], s[30:31] offset:1024
	global_store_dwordx2 v2, v[60:61], s[30:31] offset:1088
	s_waitcnt vmcnt(42)
	s_lshl_b32 s0, s12, 3
	s_add_u32 s0, s0, 6
	v_mov_b32_e32 v63, s0
	v_cndmask_b32_e64 v63, v63, v14, s[10:11]
	v_lshl_add_u32 v62, v63, 6, v9
	ds_read_b128 v[50:53], v62 offset:18432
	ds_read_b128 v[54:57], v62 offset:22528
	v_lshlrev_b32_e32 v32, 16, v88
	v_and_b32_e32 v33, 0xffff0000, v88
	v_lshlrev_b32_e32 v34, 16, v89
	v_and_b32_e32 v35, 0xffff0000, v89
	v_lshlrev_b32_e32 v36, 16, v90
	v_and_b32_e32 v37, 0xffff0000, v90
	v_lshlrev_b32_e32 v38, 16, v91
	v_and_b32_e32 v39, 0xffff0000, v91
	v_pk_mul_f32 v[40:41], v[32:33], v[32:33]
	v_pk_fma_f32 v[40:41], v[34:35], v[34:35], v[40:41]
	v_pk_fma_f32 v[40:41], v[36:37], v[36:37], v[40:41]
	v_pk_fma_f32 v[40:41], v[38:39], v[38:39], v[40:41]
	v_add_f32_e32 v40, v40, v41
	s_nop 1
	v_add_f32_dpp v40, v40, v40 quad_perm:[1,0,3,2] row_mask:0xf bank_mask:0xf
	s_nop 1
	v_add_f32_dpp v40, v40, v40 quad_perm:[2,3,0,1] row_mask:0xf bank_mask:0xf
	s_nop 1
	v_add_f32_dpp v40, v40, v40 row_half_mirror row_mask:0xf bank_mask:0xf
	s_nop 1
	v_fmamk_f32 v40, v40, 0x3c800000, v10
	v_rsq_f32_e32 v40, v40
	s_nop 0
	v_pk_mul_f32 v[32:33], v[32:33], v[40:41] op_sel_hi:[1,0]
	v_pk_mul_f32 v[34:35], v[34:35], v[40:41] op_sel_hi:[1,0]
	v_pk_mul_f32 v[36:37], v[36:37], v[40:41] op_sel_hi:[1,0]
	v_pk_mul_f32 v[38:39], v[38:39], v[40:41] op_sel_hi:[1,0]
	v_pk_mul_f32 v[32:33], v[32:33], v[16:17]
	v_pk_mul_f32 v[34:35], v[34:35], v[18:19]
	v_pk_mul_f32 v[36:37], v[36:37], v[20:21]
	v_pk_mul_f32 v[38:39], v[38:39], v[22:23]
	s_waitcnt lgkmcnt(0)
	v_pk_mul_f32 v[42:43], v[36:37], v[54:55]
	v_pk_mul_f32 v[44:45], v[38:39], v[56:57]
	v_pk_mul_f32 v[46:47], v[32:33], v[54:55]
	v_pk_mul_f32 v[48:49], v[34:35], v[56:57]
	v_pk_fma_f32 v[32:33], v[32:33], v[50:51], v[42:43] neg_lo:[0,0,1] neg_hi:[0,0,1]
	v_pk_fma_f32 v[34:35], v[34:35], v[52:53], v[44:45] neg_lo:[0,0,1] neg_hi:[0,0,1]
	v_pk_fma_f32 v[36:37], v[36:37], v[50:51], v[46:47]
	v_pk_fma_f32 v[38:39], v[38:39], v[52:53], v[48:49]
	v_pk_mul_f32 v[32:33], v[32:33], v[12:13] op_sel_hi:[1,0]
	v_pk_mul_f32 v[34:35], v[34:35], v[12:13] op_sel_hi:[1,0]
	v_pk_mul_f32 v[36:37], v[36:37], v[12:13] op_sel_hi:[1,0]
	v_pk_mul_f32 v[38:39], v[38:39], v[12:13] op_sel_hi:[1,0]
	v_cvt_pk_bf16_f32 v58, v32, v33
	v_cvt_pk_bf16_f32 v59, v34, v35
	v_cvt_pk_bf16_f32 v60, v36, v37
	v_cvt_pk_bf16_f32 v61, v38, v39
	global_store_dwordx2 v2, v[58:59], s[30:31] offset:2048
	global_store_dwordx2 v2, v[60:61], s[30:31] offset:2112
	s_waitcnt vmcnt(42)
	s_lshl_b32 s0, s12, 3
	s_add_u32 s0, s0, 7
	v_mov_b32_e32 v63, s0
	v_cndmask_b32_e64 v63, v63, v14, s[10:11]
	v_lshl_add_u32 v62, v63, 6, v9
	ds_read_b128 v[50:53], v62 offset:18432
	ds_read_b128 v[54:57], v62 offset:22528
	v_lshlrev_b32_e32 v32, 16, v92
	v_and_b32_e32 v33, 0xffff0000, v92
	v_lshlrev_b32_e32 v34, 16, v93
	v_and_b32_e32 v35, 0xffff0000, v93
	v_lshlrev_b32_e32 v36, 16, v94
	v_and_b32_e32 v37, 0xffff0000, v94
	v_lshlrev_b32_e32 v38, 16, v95
	v_and_b32_e32 v39, 0xffff0000, v95
	v_pk_mul_f32 v[40:41], v[32:33], v[32:33]
	v_pk_fma_f32 v[40:41], v[34:35], v[34:35], v[40:41]
	v_pk_fma_f32 v[40:41], v[36:37], v[36:37], v[40:41]
	v_pk_fma_f32 v[40:41], v[38:39], v[38:39], v[40:41]
	v_add_f32_e32 v40, v40, v41
	s_nop 1
	v_add_f32_dpp v40, v40, v40 quad_perm:[1,0,3,2] row_mask:0xf bank_mask:0xf
	s_nop 1
	v_add_f32_dpp v40, v40, v40 quad_perm:[2,3,0,1] row_mask:0xf bank_mask:0xf
	s_nop 1
	v_add_f32_dpp v40, v40, v40 row_half_mirror row_mask:0xf bank_mask:0xf
	s_nop 1
	v_fmamk_f32 v40, v40, 0x3c800000, v10
	v_rsq_f32_e32 v40, v40
	s_nop 0
	v_pk_mul_f32 v[32:33], v[32:33], v[40:41] op_sel_hi:[1,0]
	v_pk_mul_f32 v[34:35], v[34:35], v[40:41] op_sel_hi:[1,0]
	v_pk_mul_f32 v[36:37], v[36:37], v[40:41] op_sel_hi:[1,0]
	v_pk_mul_f32 v[38:39], v[38:39], v[40:41] op_sel_hi:[1,0]
	v_pk_mul_f32 v[32:33], v[32:33], v[16:17]
	v_pk_mul_f32 v[34:35], v[34:35], v[18:19]
	v_pk_mul_f32 v[36:37], v[36:37], v[20:21]
	v_pk_mul_f32 v[38:39], v[38:39], v[22:23]
	s_waitcnt lgkmcnt(0)
; __device__ __forceinline__ bf16_t f2bf(float f) { return (bf16_t)(cvt_pk_bf16(f, 0.f) & 0xffffu); }
; __device__ __forceinline__ void prep_phase(const Ctx& X, const bf16_t* QKV, const float* qg, const float* kg, bf16_t* QP, bf16_t* KP, bf16_t* VT) {
;     ...
;         for (int rr = 0; rr < 8; ++rr) { const int tl = X.wave * 8 + rr, R = R0 + tl, t = t0 + tl;
;             const bf16_t* rowp = QKV + (size_t)R * QKVW;
;             const float pos = (f < 16) ? (float)(t >> 6) : (float)(t & 63); const float ang = pos * invf; const float rev = __builtin_amdgcn_fractf(ang * 0.15915494309189535f); const float cs = __builtin_amdgcn_cosf(rev), sn = __builtin_amdgcn_sinf(rev);
;             if (lat) {
; #pragma unroll
;                 for (int h = 0; h < 8; ++h) { const float x = bf2f(rowp[h * 64 + X.lane]); const float y = x * rsqrtf(wave_sum(x * x) * (1.0f / 64.0f) + 1e-6f) * qgl; const float pr = __shfl_xor(y, 32);
;                     const float o = X.lane < 32 ? (y * cs - pr * sn) : (pr * sn + y * cs); QP[((size_t)R * 8 + h) * 64 + X.lane] = f2bf(o * (0.125f * LOG2E)); } }
; #pragma unroll
;             for (int h = 0; h < 2; ++h) { const float x = bf2f(rowp[512 + h * 64 + X.lane]); float y = x * rsqrtf(wave_sum(x * x) * (1.0f / 64.0f) + 1e-6f) * kgl;
;                 if (lat) { const float pr = __shfl_xor(y, 32); y = X.lane < 32 ? (y * cs - pr * sn) : (pr * sn + y * cs); }
;                 KP[((size_t)(b * 2 + h) * KPL + kp0 + tl) * 64 + X.lane] = f2bf(y);
;                 vt[(h * 64 + X.lane) * 72 + tl] = rowp[640 + h * 64 + X.lane]; }
;         }
;         __syncthreads();
;         { const int row = X.tid >> 2, ch = X.tid & 3, h = row >> 6, d = row & 63;
;             const u32x4 a = *(const u32x4*)(vt + row * 72 + ch * 16), c2 = *(const u32x4*)(vt + row * 72 + ch * 16 + 8);
;             bf16_t* dp = VT + ((size_t)(b * 2 + h) * 64 + d) * KPL + kp0 + ch * 16; *(u32x4*)dp = a; *(u32x4*)(dp + 8) = c2; }
	v_pk_mul_f32 v[42:43], v[36:37], v[54:55]
	v_pk_mul_f32 v[44:45], v[38:39], v[56:57]
	v_pk_mul_f32 v[46:47], v[32:33], v[54:55]
	v_pk_mul_f32 v[48:49], v[34:35], v[56:57]
	v_pk_fma_f32 v[32:33], v[32:33], v[50:51], v[42:43] neg_lo:[0,0,1] neg_hi:[0,0,1]
	v_pk_fma_f32 v[34:35], v[34:35], v[52:53], v[44:45] neg_lo:[0,0,1] neg_hi:[0,0,1]
	v_pk_fma_f32 v[36:37], v[36:37], v[50:51], v[46:47]
	v_pk_fma_f32 v[38:39], v[38:39], v[52:53], v[48:49]
	v_pk_mul_f32 v[32:33], v[32:33], v[12:13] op_sel_hi:[1,0]
	v_pk_mul_f32 v[34:35], v[34:35], v[12:13] op_sel_hi:[1,0]
	v_pk_mul_f32 v[36:37], v[36:37], v[12:13] op_sel_hi:[1,0]
	v_pk_mul_f32 v[38:39], v[38:39], v[12:13] op_sel_hi:[1,0]
	v_cvt_pk_bf16_f32 v58, v32, v33
	v_cvt_pk_bf16_f32 v59, v34, v35
	v_cvt_pk_bf16_f32 v60, v36, v37
	v_cvt_pk_bf16_f32 v61, v38, v39
	global_store_dwordx2 v2, v[58:59], s[30:31] offset:3072
	global_store_dwordx2 v2, v[60:61], s[30:31] offset:3136
	s_waitcnt lgkmcnt(0)
	s_barrier
	ds_read_b128 v[32:35], v7
	ds_read_b128 v[36:39], v7 offset:16
	s_waitcnt lgkmcnt(0)
	global_store_dwordx4 v8, v[32:35], s[38:39]
	global_store_dwordx4 v8, v[36:39], s[38:39] offset:16
	s_cmp_lt_u32 s2, 32
	s_cbranch_scc0 .Lpp_no3
	s_mul_i32 s0, s90, 2
	s_add_u32 s28, s2, s0
	s_mul_i32 s0, s28, 0x18000
	s_mul_i32 s1, s12, 0x3000
	s_add_u32 s0, s0, s1
	s_add_u32 s4, s88, s0
	s_addc_u32 s5, s89, 0
	s_add_u32 s4, s4, 0x7500000
	s_addc_u32 s5, s5, 0
	s_add_u32 s6, s4, 0x1800
	s_addc_u32 s7, s5, 0
	global_load_dwordx2 v[104:105], v5, s[4:5]
	global_load_dwordx2 v[106:107], v5, s[4:5] offset:3072
	global_load_dwordx2 v[108:109], v5, s[6:7]
	global_load_dwordx2 v[110:111], v5, s[6:7] offset:3072
	global_load_dwordx2 v[96:97], v3, s[4:5]
	global_load_dwordx2 v[98:99], v3, s[4:5] offset:64
	global_load_dwordx2 v[100:101], v3, s[6:7]
	global_load_dwordx2 v[102:103], v3, s[6:7] offset:64
.Lpp_no3:
	s_lshr_b32 s33, s21, 6
	s_and_b32 s35, s21, 63
	s_lshl_b32 s34, s35, 6
	v_mov_b32_e32 v14, s35
	s_mul_i32 s0, s33, 0x110000
	s_lshl_b32 s1, s12, 3
	s_add_u32 s1, s1, s34
	s_lshl_b32 s1, s1, 7
	s_add_u32 s0, s0, s1
	s_add_u32 s36, s88, s0
	s_addc_u32 s37, s89, 0
	s_add_u32 s36, s36, 0x17400000
	s_addc_u32 s37, s37, 0
	s_mul_i32 s0, s33, 0x110000
	s_lshl_b32 s1, s34, 1
	s_add_u32 s0, s0, s1
	s_add_u32 s38, s88, s0
	s_addc_u32 s39, s89, 0
	s_add_u32 s38, s38, 0x17d00000
	s_addc_u32 s39, s39, 0
	s_lshl_b32 s0, s21, 16
	s_lshl_b32 s1, s12, 13
	s_add_u32 s0, s0, s1
	s_add_u32 s30, s88, s0
	s_addc_u32 s31, s89, 0
	s_add_u32 s30, s30, 0x10d00000
	s_addc_u32 s31, s31, 0
	s_barrier
	s_waitcnt vmcnt(42)
	ds_write_b16 v6, v152 offset:0
	ds_write_b16_d16_hi v6, v152 offset:144
	ds_write_b16 v6, v153 offset:288
	ds_write_b16_d16_hi v6, v153 offset:432
	ds_write_b16 v6, v154 offset:4
	ds_write_b16_d16_hi v6, v154 offset:148
	ds_write_b16 v6, v155 offset:292
	ds_write_b16_d16_hi v6, v155 offset:436
	ds_write_b16 v6, v156 offset:8
	ds_write_b16_d16_hi v6, v156 offset:152
	ds_write_b16 v6, v157 offset:296
	ds_write_b16_d16_hi v6, v157 offset:440
	ds_write_b16 v6, v158 offset:12
	ds_write_b16_d16_hi v6, v158 offset:156
	ds_write_b16 v6, v159 offset:300
	ds_write_b16_d16_hi v6, v159 offset:444
	s_waitcnt vmcnt(40)
	s_lshl_b32 s0, s12, 3
	s_add_u32 s0, s0, 0
	v_add_u32_e32 v63, s0, v15
	v_cndmask_b32_e64 v63, v63, v14, s[10:11]
	v_lshl_add_u32 v62, v63, 6, v9
	ds_read_b128 v[50:53], v62 offset:18432
	ds_read_b128 v[54:57], v62 offset:22528
	v_lshlrev_b32_e32 v32, 16, v144
	v_and_b32_e32 v33, 0xffff0000, v144
	v_lshlrev_b32_e32 v34, 16, v145
	v_and_b32_e32 v35, 0xffff0000, v145
	v_lshlrev_b32_e32 v36, 16, v146
	v_and_b32_e32 v37, 0xffff0000, v146
	v_lshlrev_b32_e32 v38, 16, v147
	v_and_b32_e32 v39, 0xffff0000, v147
	v_pk_mul_f32 v[40:41], v[32:33], v[32:33]
	v_pk_fma_f32 v[40:41], v[34:35], v[34:35], v[40:41]
	v_pk_fma_f32 v[40:41], v[36:37], v[36:37], v[40:41]
	v_pk_fma_f32 v[40:41], v[38:39], v[38:39], v[40:41]
	v_add_f32_e32 v40, v40, v41
	s_nop 1
	v_add_f32_dpp v40, v40, v40 quad_perm:[1,0,3,2] row_mask:0xf bank_mask:0xf
	s_nop 1
	v_add_f32_dpp v40, v40, v40 quad_perm:[2,3,0,1] row_mask:0xf bank_mask:0xf
	s_nop 1
	v_add_f32_dpp v40, v40, v40 row_half_mirror row_mask:0xf bank_mask:0xf
	s_nop 1
	v_fmamk_f32 v40, v40, 0x3c800000, v10
	v_rsq_f32_e32 v40, v40
	s_nop 0
	v_pk_mul_f32 v[32:33], v[32:33], v[40:41] op_sel_hi:[1,0]
	v_pk_mul_f32 v[34:35], v[34:35], v[40:41] op_sel_hi:[1,0]
	v_pk_mul_f32 v[36:37], v[36:37], v[40:41] op_sel_hi:[1,0]
	v_pk_mul_f32 v[38:39], v[38:39], v[40:41] op_sel_hi:[1,0]
	v_pk_mul_f32 v[32:33], v[32:33], v[24:25]
	v_pk_mul_f32 v[34:35], v[34:35], v[26:27]
	v_pk_mul_f32 v[36:37], v[36:37], v[28:29]
	v_pk_mul_f32 v[38:39], v[38:39], v[30:31]
	s_waitcnt lgkmcnt(0)
	v_pk_mul_f32 v[42:43], v[36:37], v[54:55]
	v_pk_mul_f32 v[44:45], v[38:39], v[56:57]
	v_pk_mul_f32 v[46:47], v[32:33], v[54:55]
	v_pk_mul_f32 v[48:49], v[34:35], v[56:57]
	v_pk_fma_f32 v[32:33], v[32:33], v[50:51], v[42:43] neg_lo:[0,0,1] neg_hi:[0,0,1]
	v_pk_fma_f32 v[34:35], v[34:35], v[52:53], v[44:45] neg_lo:[0,0,1] neg_hi:[0,0,1]
	v_pk_fma_f32 v[36:37], v[36:37], v[50:51], v[46:47]
	v_pk_fma_f32 v[38:39], v[38:39], v[52:53], v[48:49]
	v_cvt_pk_bf16_f32 v58, v32, v33
	v_cvt_pk_bf16_f32 v59, v34, v35
	v_cvt_pk_bf16_f32 v60, v36, v37
	v_cvt_pk_bf16_f32 v61, v38, v39
	global_store_dwordx2 v4, v[58:59], s[36:37]
	global_store_dwordx2 v4, v[60:61], s[36:37] offset:64
	s_waitcnt vmcnt(40)
; __device__ __forceinline__ bf16_t f2bf(float f) { return (bf16_t)(cvt_pk_bf16(f, 0.f) & 0xffffu); }
; __device__ __forceinline__ void prep_phase(const Ctx& X, const bf16_t* QKV, const float* qg, const float* kg, bf16_t* QP, bf16_t* KP, bf16_t* VT) {
;     ...
;             const float pos = (f < 16) ? (float)(t >> 6) : (float)(t & 63); const float ang = pos * invf; const float rev = __builtin_amdgcn_fractf(ang * 0.15915494309189535f); const float cs = __builtin_amdgcn_cosf(rev), sn = __builtin_amdgcn_sinf(rev);
;             if (lat) {
; #pragma unroll
;                 for (int h = 0; h < 8; ++h) { const float x = bf2f(rowp[h * 64 + X.lane]); const float y = x * rsqrtf(wave_sum(x * x) * (1.0f / 64.0f) + 1e-6f) * qgl; const float pr = __shfl_xor(y, 32);
;                     const float o = X.lane < 32 ? (y * cs - pr * sn) : (pr * sn + y * cs); QP[((size_t)R * 8 + h) * 64 + X.lane] = f2bf(o * (0.125f * LOG2E)); } }
; #pragma unroll
;             for (int h = 0; h < 2; ++h) { const float x = bf2f(rowp[512 + h * 64 + X.lane]); float y = x * rsqrtf(wave_sum(x * x) * (1.0f / 64.0f) + 1e-6f) * kgl;
;                 if (lat) { const float pr = __shfl_xor(y, 32); y = X.lane < 32 ? (y * cs - pr * sn) : (pr * sn + y * cs); }
;                 KP[((size_t)(b * 2 + h) * KPL + kp0 + tl) * 64 + X.lane] = f2bf(y);
	s_lshl_b32 s0, s12, 3
	s_add_u32 s0, s0, 4
	v_add_u32_e32 v63, s0, v15
	v_cndmask_b32_e64 v63, v63, v14, s[10:11]
	v_lshl_add_u32 v62, v63, 6, v9
	ds_read_b128 v[50:53], v62 offset:18432
	ds_read_b128 v[54:57], v62 offset:22528
	v_lshlrev_b32_e32 v32, 16, v148
	v_and_b32_e32 v33, 0xffff0000, v148
	v_lshlrev_b32_e32 v34, 16, v149
	v_and_b32_e32 v35, 0xffff0000, v149
	v_lshlrev_b32_e32 v36, 16, v150
	v_and_b32_e32 v37, 0xffff0000, v150
	v_lshlrev_b32_e32 v38, 16, v151
	v_and_b32_e32 v39, 0xffff0000, v151
	v_pk_mul_f32 v[40:41], v[32:33], v[32:33]
	v_pk_fma_f32 v[40:41], v[34:35], v[34:35], v[40:41]
	v_pk_fma_f32 v[40:41], v[36:37], v[36:37], v[40:41]
	v_pk_fma_f32 v[40:41], v[38:39], v[38:39], v[40:41]
	v_add_f32_e32 v40, v40, v41
	s_nop 1
	v_add_f32_dpp v40, v40, v40 quad_perm:[1,0,3,2] row_mask:0xf bank_mask:0xf
	s_nop 1
	v_add_f32_dpp v40, v40, v40 quad_perm:[2,3,0,1] row_mask:0xf bank_mask:0xf
	s_nop 1
	v_add_f32_dpp v40, v40, v40 row_half_mirror row_mask:0xf bank_mask:0xf
	s_nop 1
	v_fmamk_f32 v40, v40, 0x3c800000, v10
	v_rsq_f32_e32 v40, v40
	s_nop 0
	v_pk_mul_f32 v[32:33], v[32:33], v[40:41] op_sel_hi:[1,0]
	v_pk_mul_f32 v[34:35], v[34:35], v[40:41] op_sel_hi:[1,0]
	v_pk_mul_f32 v[36:37], v[36:37], v[40:41] op_sel_hi:[1,0]
	v_pk_mul_f32 v[38:39], v[38:39], v[40:41] op_sel_hi:[1,0]
	v_pk_mul_f32 v[32:33], v[32:33], v[24:25]
	v_pk_mul_f32 v[34:35], v[34:35], v[26:27]
	v_pk_mul_f32 v[36:37], v[36:37], v[28:29]
	v_pk_mul_f32 v[38:39], v[38:39], v[30:31]
	s_waitcnt lgkmcnt(0)
	v_pk_mul_f32 v[42:43], v[36:37], v[54:55]
	v_pk_mul_f32 v[44:45], v[38:39], v[56:57]
	v_pk_mul_f32 v[46:47], v[32:33], v[54:55]
	v_pk_mul_f32 v[48:49], v[34:35], v[56:57]
	v_pk_fma_f32 v[32:33], v[32:33], v[50:51], v[42:43] neg_lo:[0,0,1] neg_hi:[0,0,1]
	v_pk_fma_f32 v[34:35], v[34:35], v[52:53], v[44:45] neg_lo:[0,0,1] neg_hi:[0,0,1]
	v_pk_fma_f32 v[36:37], v[36:37], v[50:51], v[46:47]
	v_pk_fma_f32 v[38:39], v[38:39], v[52:53], v[48:49]
	v_cvt_pk_bf16_f32 v58, v32, v33
	v_cvt_pk_bf16_f32 v59, v34, v35
	v_cvt_pk_bf16_f32 v60, v36, v37
	v_cvt_pk_bf16_f32 v61, v38, v39
	global_store_dwordx2 v4, v[58:59], s[36:37] offset:512
	global_store_dwordx2 v4, v[60:61], s[36:37] offset:576
	s_waitcnt vmcnt(40)
	s_lshl_b32 s0, s12, 3
	v_mov_b32_e32 v63, s0
	v_cndmask_b32_e64 v63, v63, v14, s[10:11]
	v_lshl_add_u32 v62, v63, 6, v9
	ds_read_b128 v[50:53], v62 offset:18432
	ds_read_b128 v[54:57], v62 offset:22528
	v_lshlrev_b32_e32 v32, 16, v112
	v_and_b32_e32 v33, 0xffff0000, v112
	v_lshlrev_b32_e32 v34, 16, v113
	v_and_b32_e32 v35, 0xffff0000, v113
	v_lshlrev_b32_e32 v36, 16, v114
	v_and_b32_e32 v37, 0xffff0000, v114
	v_lshlrev_b32_e32 v38, 16, v115
	v_and_b32_e32 v39, 0xffff0000, v115
	v_pk_mul_f32 v[40:41], v[32:33], v[32:33]
	v_pk_fma_f32 v[40:41], v[34:35], v[34:35], v[40:41]
	v_pk_fma_f32 v[40:41], v[36:37], v[36:37], v[40:41]
	v_pk_fma_f32 v[40:41], v[38:39], v[38:39], v[40:41]
	v_add_f32_e32 v40, v40, v41
	s_nop 1
	v_add_f32_dpp v40, v40, v40 quad_perm:[1,0,3,2] row_mask:0xf bank_mask:0xf
	s_nop 1
	v_add_f32_dpp v40, v40, v40 quad_perm:[2,3,0,1] row_mask:0xf bank_mask:0xf
	s_nop 1
	v_add_f32_dpp v40, v40, v40 row_half_mirror row_mask:0xf bank_mask:0xf
	s_nop 1
	v_fmamk_f32 v40, v40, 0x3c800000, v10
	v_rsq_f32_e32 v40, v40
	s_nop 0
	v_pk_mul_f32 v[32:33], v[32:33], v[40:41] op_sel_hi:[1,0]
	v_pk_mul_f32 v[34:35], v[34:35], v[40:41] op_sel_hi:[1,0]
	v_pk_mul_f32 v[36:37], v[36:37], v[40:41] op_sel_hi:[1,0]
	v_pk_mul_f32 v[38:39], v[38:39], v[40:41] op_sel_hi:[1,0]
	v_pk_mul_f32 v[32:33], v[32:33], v[16:17]
	v_pk_mul_f32 v[34:35], v[34:35], v[18:19]
	v_pk_mul_f32 v[36:37], v[36:37], v[20:21]
	v_pk_mul_f32 v[38:39], v[38:39], v[22:23]
	s_waitcnt lgkmcnt(0)
	v_pk_mul_f32 v[42:43], v[36:37], v[54:55]
	v_pk_mul_f32 v[44:45], v[38:39], v[56:57]
	v_pk_mul_f32 v[46:47], v[32:33], v[54:55]
	v_pk_mul_f32 v[48:49], v[34:35], v[56:57]
	v_pk_fma_f32 v[32:33], v[32:33], v[50:51], v[42:43] neg_lo:[0,0,1] neg_hi:[0,0,1]
	v_pk_fma_f32 v[34:35], v[34:35], v[52:53], v[44:45] neg_lo:[0,0,1] neg_hi:[0,0,1]
	v_pk_fma_f32 v[36:37], v[36:37], v[50:51], v[46:47]
	v_pk_fma_f32 v[38:39], v[38:39], v[52:53], v[48:49]
	v_pk_mul_f32 v[32:33], v[32:33], v[12:13] op_sel_hi:[1,0]
	v_pk_mul_f32 v[34:35], v[34:35], v[12:13] op_sel_hi:[1,0]
	v_pk_mul_f32 v[36:37], v[36:37], v[12:13] op_sel_hi:[1,0]
	v_pk_mul_f32 v[38:39], v[38:39], v[12:13] op_sel_hi:[1,0]
	v_cvt_pk_bf16_f32 v58, v32, v33
	v_cvt_pk_bf16_f32 v59, v34, v35
	v_cvt_pk_bf16_f32 v60, v36, v37
	v_cvt_pk_bf16_f32 v61, v38, v39
	global_store_dwordx2 v2, v[58:59], s[30:31]
	global_store_dwordx2 v2, v[60:61], s[30:31] offset:64
	s_waitcnt vmcnt(40)
	s_lshl_b32 s0, s12, 3
	s_add_u32 s0, s0, 1
	v_mov_b32_e32 v63, s0
	v_cndmask_b32_e64 v63, v63, v14, s[10:11]
	v_lshl_add_u32 v62, v63, 6, v9
	ds_read_b128 v[50:53], v62 offset:18432
	ds_read_b128 v[54:57], v62 offset:22528
	v_lshlrev_b32_e32 v32, 16, v116
	v_and_b32_e32 v33, 0xffff0000, v116
	v_lshlrev_b32_e32 v34, 16, v117
	v_and_b32_e32 v35, 0xffff0000, v117
	v_lshlrev_b32_e32 v36, 16, v118
	v_and_b32_e32 v37, 0xffff0000, v118
	v_lshlrev_b32_e32 v38, 16, v119
	v_and_b32_e32 v39, 0xffff0000, v119
	v_pk_mul_f32 v[40:41], v[32:33], v[32:33]
	v_pk_fma_f32 v[40:41], v[34:35], v[34:35], v[40:41]
	v_pk_fma_f32 v[40:41], v[36:37], v[36:37], v[40:41]
	v_pk_fma_f32 v[40:41], v[38:39], v[38:39], v[40:41]
	v_add_f32_e32 v40, v40, v41
	s_nop 1
	v_add_f32_dpp v40, v40, v40 quad_perm:[1,0,3,2] row_mask:0xf bank_mask:0xf
	s_nop 1
	v_add_f32_dpp v40, v40, v40 quad_perm:[2,3,0,1] row_mask:0xf bank_mask:0xf
	s_nop 1
	v_add_f32_dpp v40, v40, v40 row_half_mirror row_mask:0xf bank_mask:0xf
	s_nop 1
	v_fmamk_f32 v40, v40, 0x3c800000, v10
	v_rsq_f32_e32 v40, v40
	s_nop 0
	v_pk_mul_f32 v[32:33], v[32:33], v[40:41] op_sel_hi:[1,0]
	v_pk_mul_f32 v[34:35], v[34:35], v[40:41] op_sel_hi:[1,0]
	v_pk_mul_f32 v[36:37], v[36:37], v[40:41] op_sel_hi:[1,0]
	v_pk_mul_f32 v[38:39], v[38:39], v[40:41] op_sel_hi:[1,0]
	v_pk_mul_f32 v[32:33], v[32:33], v[16:17]
	v_pk_mul_f32 v[34:35], v[34:35], v[18:19]
	v_pk_mul_f32 v[36:37], v[36:37], v[20:21]
	v_pk_mul_f32 v[38:39], v[38:39], v[22:23]
	s_waitcnt lgkmcnt(0)
; __device__ __forceinline__ bf16_t f2bf(float f) { return (bf16_t)(cvt_pk_bf16(f, 0.f) & 0xffffu); }
; __device__ __forceinline__ void prep_phase(const Ctx& X, const bf16_t* QKV, const float* qg, const float* kg, bf16_t* QP, bf16_t* KP, bf16_t* VT) {
;     ...
;             const float pos = (f < 16) ? (float)(t >> 6) : (float)(t & 63); const float ang = pos * invf; const float rev = __builtin_amdgcn_fractf(ang * 0.15915494309189535f); const float cs = __builtin_amdgcn_cosf(rev), sn = __builtin_amdgcn_sinf(rev);
;             if (lat) {
; #pragma unroll
;                 for (int h = 0; h < 8; ++h) { const float x = bf2f(rowp[h * 64 + X.lane]); const float y = x * rsqrtf(wave_sum(x * x) * (1.0f / 64.0f) + 1e-6f) * qgl; const float pr = __shfl_xor(y, 32);
;                     const float o = X.lane < 32 ? (y * cs - pr * sn) : (pr * sn + y * cs); QP[((size_t)R * 8 + h) * 64 + X.lane] = f2bf(o * (0.125f * LOG2E)); } }
	v_pk_mul_f32 v[42:43], v[36:37], v[54:55]
	v_pk_mul_f32 v[44:45], v[38:39], v[56:57]
	v_pk_mul_f32 v[46:47], v[32:33], v[54:55]
	v_pk_mul_f32 v[48:49], v[34:35], v[56:57]
	v_pk_fma_f32 v[32:33], v[32:33], v[50:51], v[42:43] neg_lo:[0,0,1] neg_hi:[0,0,1]
	v_pk_fma_f32 v[34:35], v[34:35], v[52:53], v[44:45] neg_lo:[0,0,1] neg_hi:[0,0,1]
	v_pk_fma_f32 v[36:37], v[36:37], v[50:51], v[46:47]
	v_pk_fma_f32 v[38:39], v[38:39], v[52:53], v[48:49]
	v_pk_mul_f32 v[32:33], v[32:33], v[12:13] op_sel_hi:[1,0]
	v_pk_mul_f32 v[34:35], v[34:35], v[12:13] op_sel_hi:[1,0]
	v_pk_mul_f32 v[36:37], v[36:37], v[12:13] op_sel_hi:[1,0]
	v_pk_mul_f32 v[38:39], v[38:39], v[12:13] op_sel_hi:[1,0]
	v_cvt_pk_bf16_f32 v58, v32, v33
	v_cvt_pk_bf16_f32 v59, v34, v35
	v_cvt_pk_bf16_f32 v60, v36, v37
	v_cvt_pk_bf16_f32 v61, v38, v39
	global_store_dwordx2 v2, v[58:59], s[30:31] offset:1024
	global_store_dwordx2 v2, v[60:61], s[30:31] offset:1088
	s_waitcnt vmcnt(40)
	s_lshl_b32 s0, s12, 3
	s_add_u32 s0, s0, 2
	v_mov_b32_e32 v63, s0
	v_cndmask_b32_e64 v63, v63, v14, s[10:11]
	v_lshl_add_u32 v62, v63, 6, v9
	ds_read_b128 v[50:53], v62 offset:18432
	ds_read_b128 v[54:57], v62 offset:22528
	v_lshlrev_b32_e32 v32, 16, v120
	v_and_b32_e32 v33, 0xffff0000, v120
	v_lshlrev_b32_e32 v34, 16, v121
	v_and_b32_e32 v35, 0xffff0000, v121
	v_lshlrev_b32_e32 v36, 16, v122
	v_and_b32_e32 v37, 0xffff0000, v122
	v_lshlrev_b32_e32 v38, 16, v123
	v_and_b32_e32 v39, 0xffff0000, v123
	v_pk_mul_f32 v[40:41], v[32:33], v[32:33]
	v_pk_fma_f32 v[40:41], v[34:35], v[34:35], v[40:41]
	v_pk_fma_f32 v[40:41], v[36:37], v[36:37], v[40:41]
	v_pk_fma_f32 v[40:41], v[38:39], v[38:39], v[40:41]
	v_add_f32_e32 v40, v40, v41
	s_nop 1
	v_add_f32_dpp v40, v40, v40 quad_perm:[1,0,3,2] row_mask:0xf bank_mask:0xf
	s_nop 1
	v_add_f32_dpp v40, v40, v40 quad_perm:[2,3,0,1] row_mask:0xf bank_mask:0xf
	s_nop 1
	v_add_f32_dpp v40, v40, v40 row_half_mirror row_mask:0xf bank_mask:0xf
	s_nop 1
	v_fmamk_f32 v40, v40, 0x3c800000, v10
	v_rsq_f32_e32 v40, v40
	s_nop 0
	v_pk_mul_f32 v[32:33], v[32:33], v[40:41] op_sel_hi:[1,0]
	v_pk_mul_f32 v[34:35], v[34:35], v[40:41] op_sel_hi:[1,0]
	v_pk_mul_f32 v[36:37], v[36:37], v[40:41] op_sel_hi:[1,0]
	v_pk_mul_f32 v[38:39], v[38:39], v[40:41] op_sel_hi:[1,0]
	v_pk_mul_f32 v[32:33], v[32:33], v[16:17]
	v_pk_mul_f32 v[34:35], v[34:35], v[18:19]
	v_pk_mul_f32 v[36:37], v[36:37], v[20:21]
	v_pk_mul_f32 v[38:39], v[38:39], v[22:23]
	s_waitcnt lgkmcnt(0)
	v_pk_mul_f32 v[42:43], v[36:37], v[54:55]
	v_pk_mul_f32 v[44:45], v[38:39], v[56:57]
	v_pk_mul_f32 v[46:47], v[32:33], v[54:55]
	v_pk_mul_f32 v[48:49], v[34:35], v[56:57]
	v_pk_fma_f32 v[32:33], v[32:33], v[50:51], v[42:43] neg_lo:[0,0,1] neg_hi:[0,0,1]
	v_pk_fma_f32 v[34:35], v[34:35], v[52:53], v[44:45] neg_lo:[0,0,1] neg_hi:[0,0,1]
	v_pk_fma_f32 v[36:37], v[36:37], v[50:51], v[46:47]
	v_pk_fma_f32 v[38:39], v[38:39], v[52:53], v[48:49]
	v_pk_mul_f32 v[32:33], v[32:33], v[12:13] op_sel_hi:[1,0]
	v_pk_mul_f32 v[34:35], v[34:35], v[12:13] op_sel_hi:[1,0]
	v_pk_mul_f32 v[36:37], v[36:37], v[12:13] op_sel_hi:[1,0]
	v_pk_mul_f32 v[38:39], v[38:39], v[12:13] op_sel_hi:[1,0]
	v_cvt_pk_bf16_f32 v58, v32, v33
	v_cvt_pk_bf16_f32 v59, v34, v35
	v_cvt_pk_bf16_f32 v60, v36, v37
	v_cvt_pk_bf16_f32 v61, v38, v39
	global_store_dwordx2 v2, v[58:59], s[30:31] offset:2048
	global_store_dwordx2 v2, v[60:61], s[30:31] offset:2112
	s_waitcnt vmcnt(40)
	s_lshl_b32 s0, s12, 3
	s_add_u32 s0, s0, 3
	v_mov_b32_e32 v63, s0
	v_cndmask_b32_e64 v63, v63, v14, s[10:11]
	v_lshl_add_u32 v62, v63, 6, v9
	ds_read_b128 v[50:53], v62 offset:18432
	ds_read_b128 v[54:57], v62 offset:22528
	v_lshlrev_b32_e32 v32, 16, v124
	v_and_b32_e32 v33, 0xffff0000, v124
	v_lshlrev_b32_e32 v34, 16, v125
	v_and_b32_e32 v35, 0xffff0000, v125
	v_lshlrev_b32_e32 v36, 16, v126
	v_and_b32_e32 v37, 0xffff0000, v126
	v_lshlrev_b32_e32 v38, 16, v127
	v_and_b32_e32 v39, 0xffff0000, v127
	v_pk_mul_f32 v[40:41], v[32:33], v[32:33]
	v_pk_fma_f32 v[40:41], v[34:35], v[34:35], v[40:41]
	v_pk_fma_f32 v[40:41], v[36:37], v[36:37], v[40:41]
	v_pk_fma_f32 v[40:41], v[38:39], v[38:39], v[40:41]
	v_add_f32_e32 v40, v40, v41
	s_nop 1
	v_add_f32_dpp v40, v40, v40 quad_perm:[1,0,3,2] row_mask:0xf bank_mask:0xf
	s_nop 1
	v_add_f32_dpp v40, v40, v40 quad_perm:[2,3,0,1] row_mask:0xf bank_mask:0xf
	s_nop 1
	v_add_f32_dpp v40, v40, v40 row_half_mirror row_mask:0xf bank_mask:0xf
	s_nop 1
	v_fmamk_f32 v40, v40, 0x3c800000, v10
	v_rsq_f32_e32 v40, v40
	s_nop 0
	v_pk_mul_f32 v[32:33], v[32:33], v[40:41] op_sel_hi:[1,0]
	v_pk_mul_f32 v[34:35], v[34:35], v[40:41] op_sel_hi:[1,0]
	v_pk_mul_f32 v[36:37], v[36:37], v[40:41] op_sel_hi:[1,0]
	v_pk_mul_f32 v[38:39], v[38:39], v[40:41] op_sel_hi:[1,0]
	v_pk_mul_f32 v[32:33], v[32:33], v[16:17]
	v_pk_mul_f32 v[34:35], v[34:35], v[18:19]
	v_pk_mul_f32 v[36:37], v[36:37], v[20:21]
	v_pk_mul_f32 v[38:39], v[38:39], v[22:23]
	s_waitcnt lgkmcnt(0)
	v_pk_mul_f32 v[42:43], v[36:37], v[54:55]
	v_pk_mul_f32 v[44:45], v[38:39], v[56:57]
	v_pk_mul_f32 v[46:47], v[32:33], v[54:55]
	v_pk_mul_f32 v[48:49], v[34:35], v[56:57]
	v_pk_fma_f32 v[32:33], v[32:33], v[50:51], v[42:43] neg_lo:[0,0,1] neg_hi:[0,0,1]
	v_pk_fma_f32 v[34:35], v[34:35], v[52:53], v[44:45] neg_lo:[0,0,1] neg_hi:[0,0,1]
	v_pk_fma_f32 v[36:37], v[36:37], v[50:51], v[46:47]
	v_pk_fma_f32 v[38:39], v[38:39], v[52:53], v[48:49]
	v_pk_mul_f32 v[32:33], v[32:33], v[12:13] op_sel_hi:[1,0]
	v_pk_mul_f32 v[34:35], v[34:35], v[12:13] op_sel_hi:[1,0]
	v_pk_mul_f32 v[36:37], v[36:37], v[12:13] op_sel_hi:[1,0]
	v_pk_mul_f32 v[38:39], v[38:39], v[12:13] op_sel_hi:[1,0]
	v_cvt_pk_bf16_f32 v58, v32, v33
	v_cvt_pk_bf16_f32 v59, v34, v35
	v_cvt_pk_bf16_f32 v60, v36, v37
	v_cvt_pk_bf16_f32 v61, v38, v39
	global_store_dwordx2 v2, v[58:59], s[30:31] offset:3072
	global_store_dwordx2 v2, v[60:61], s[30:31] offset:3136
	s_waitcnt vmcnt(40)
; __device__ __forceinline__ bf16_t f2bf(float f) { return (bf16_t)(cvt_pk_bf16(f, 0.f) & 0xffffu); }
; __device__ __forceinline__ void prep_phase(const Ctx& X, const bf16_t* QKV, const float* qg, const float* kg, bf16_t* QP, bf16_t* KP, bf16_t* VT) {
;     ...
;             const float pos = (f < 16) ? (float)(t >> 6) : (float)(t & 63); const float ang = pos * invf; const float rev = __builtin_amdgcn_fractf(ang * 0.15915494309189535f); const float cs = __builtin_amdgcn_cosf(rev), sn = __builtin_amdgcn_sinf(rev);
;             if (lat) {
; #pragma unroll
;                 for (int h = 0; h < 8; ++h) { const float x = bf2f(rowp[h * 64 + X.lane]); const float y = x * rsqrtf(wave_sum(x * x) * (1.0f / 64.0f) + 1e-6f) * qgl; const float pr = __shfl_xor(y, 32);
;                     const float o = X.lane < 32 ? (y * cs - pr * sn) : (pr * sn + y * cs); QP[((size_t)R * 8 + h) * 64 + X.lane] = f2bf(o * (0.125f * LOG2E)); } }
	s_lshl_b32 s0, s12, 3
	s_add_u32 s0, s0, 4
	v_mov_b32_e32 v63, s0
	v_cndmask_b32_e64 v63, v63, v14, s[10:11]
	v_lshl_add_u32 v62, v63, 6, v9
	ds_read_b128 v[50:53], v62 offset:18432
	ds_read_b128 v[54:57], v62 offset:22528
	v_lshlrev_b32_e32 v32, 16, v128
	v_and_b32_e32 v33, 0xffff0000, v128
	v_lshlrev_b32_e32 v34, 16, v129
	v_and_b32_e32 v35, 0xffff0000, v129
	v_lshlrev_b32_e32 v36, 16, v130
	v_and_b32_e32 v37, 0xffff0000, v130
	v_lshlrev_b32_e32 v38, 16, v131
	v_and_b32_e32 v39, 0xffff0000, v131
	v_pk_mul_f32 v[40:41], v[32:33], v[32:33]
	v_pk_fma_f32 v[40:41], v[34:35], v[34:35], v[40:41]
	v_pk_fma_f32 v[40:41], v[36:37], v[36:37], v[40:41]
	v_pk_fma_f32 v[40:41], v[38:39], v[38:39], v[40:41]
	v_add_f32_e32 v40, v40, v41
	s_nop 1
	v_add_f32_dpp v40, v40, v40 quad_perm:[1,0,3,2] row_mask:0xf bank_mask:0xf
	s_nop 1
	v_add_f32_dpp v40, v40, v40 quad_perm:[2,3,0,1] row_mask:0xf bank_mask:0xf
	s_nop 1
	v_add_f32_dpp v40, v40, v40 row_half_mirror row_mask:0xf bank_mask:0xf
	s_nop 1
	v_fmamk_f32 v40, v40, 0x3c800000, v10
	v_rsq_f32_e32 v40, v40
	s_nop 0
	v_pk_mul_f32 v[32:33], v[32:33], v[40:41] op_sel_hi:[1,0]
	v_pk_mul_f32 v[34:35], v[34:35], v[40:41] op_sel_hi:[1,0]
	v_pk_mul_f32 v[36:37], v[36:37], v[40:41] op_sel_hi:[1,0]
	v_pk_mul_f32 v[38:39], v[38:39], v[40:41] op_sel_hi:[1,0]
	v_pk_mul_f32 v[32:33], v[32:33], v[16:17]
	v_pk_mul_f32 v[34:35], v[34:35], v[18:19]
	v_pk_mul_f32 v[36:37], v[36:37], v[20:21]
	v_pk_mul_f32 v[38:39], v[38:39], v[22:23]
	s_waitcnt lgkmcnt(0)
	v_pk_mul_f32 v[42:43], v[36:37], v[54:55]
	v_pk_mul_f32 v[44:45], v[38:39], v[56:57]
	v_pk_mul_f32 v[46:47], v[32:33], v[54:55]
	v_pk_mul_f32 v[48:49], v[34:35], v[56:57]
	v_pk_fma_f32 v[32:33], v[32:33], v[50:51], v[42:43] neg_lo:[0,0,1] neg_hi:[0,0,1]
	v_pk_fma_f32 v[34:35], v[34:35], v[52:53], v[44:45] neg_lo:[0,0,1] neg_hi:[0,0,1]
	v_pk_fma_f32 v[36:37], v[36:37], v[50:51], v[46:47]
	v_pk_fma_f32 v[38:39], v[38:39], v[52:53], v[48:49]
	v_pk_mul_f32 v[32:33], v[32:33], v[12:13] op_sel_hi:[1,0]
	v_pk_mul_f32 v[34:35], v[34:35], v[12:13] op_sel_hi:[1,0]
	v_pk_mul_f32 v[36:37], v[36:37], v[12:13] op_sel_hi:[1,0]
	v_pk_mul_f32 v[38:39], v[38:39], v[12:13] op_sel_hi:[1,0]
	v_cvt_pk_bf16_f32 v58, v32, v33
	v_cvt_pk_bf16_f32 v59, v34, v35
	v_cvt_pk_bf16_f32 v60, v36, v37
	v_cvt_pk_bf16_f32 v61, v38, v39
	s_add_u32 s30, s30, 0x1000
	s_addc_u32 s31, s31, 0
	global_store_dwordx2 v2, v[58:59], s[30:31]
	global_store_dwordx2 v2, v[60:61], s[30:31] offset:64
	s_waitcnt vmcnt(40)
	s_lshl_b32 s0, s12, 3
	s_add_u32 s0, s0, 5
	v_mov_b32_e32 v63, s0
	v_cndmask_b32_e64 v63, v63, v14, s[10:11]
	v_lshl_add_u32 v62, v63, 6, v9
	ds_read_b128 v[50:53], v62 offset:18432
	ds_read_b128 v[54:57], v62 offset:22528
	v_lshlrev_b32_e32 v32, 16, v132
	v_and_b32_e32 v33, 0xffff0000, v132
	v_lshlrev_b32_e32 v34, 16, v133
	v_and_b32_e32 v35, 0xffff0000, v133
	v_lshlrev_b32_e32 v36, 16, v134
	v_and_b32_e32 v37, 0xffff0000, v134
	v_lshlrev_b32_e32 v38, 16, v135
	v_and_b32_e32 v39, 0xffff0000, v135
	v_pk_mul_f32 v[40:41], v[32:33], v[32:33]
	v_pk_fma_f32 v[40:41], v[34:35], v[34:35], v[40:41]
	v_pk_fma_f32 v[40:41], v[36:37], v[36:37], v[40:41]
	v_pk_fma_f32 v[40:41], v[38:39], v[38:39], v[40:41]
	v_add_f32_e32 v40, v40, v41
	s_nop 1
	v_add_f32_dpp v40, v40, v40 quad_perm:[1,0,3,2] row_mask:0xf bank_mask:0xf
	s_nop 1
	v_add_f32_dpp v40, v40, v40 quad_perm:[2,3,0,1] row_mask:0xf bank_mask:0xf
	s_nop 1
	v_add_f32_dpp v40, v40, v40 row_half_mirror row_mask:0xf bank_mask:0xf
	s_nop 1
	v_fmamk_f32 v40, v40, 0x3c800000, v10
	v_rsq_f32_e32 v40, v40
	s_nop 0
	v_pk_mul_f32 v[32:33], v[32:33], v[40:41] op_sel_hi:[1,0]
	v_pk_mul_f32 v[34:35], v[34:35], v[40:41] op_sel_hi:[1,0]
	v_pk_mul_f32 v[36:37], v[36:37], v[40:41] op_sel_hi:[1,0]
	v_pk_mul_f32 v[38:39], v[38:39], v[40:41] op_sel_hi:[1,0]
	v_pk_mul_f32 v[32:33], v[32:33], v[16:17]
	v_pk_mul_f32 v[34:35], v[34:35], v[18:19]
	v_pk_mul_f32 v[36:37], v[36:37], v[20:21]
	v_pk_mul_f32 v[38:39], v[38:39], v[22:23]
	s_waitcnt lgkmcnt(0)
	v_pk_mul_f32 v[42:43], v[36:37], v[54:55]
	v_pk_mul_f32 v[44:45], v[38:39], v[56:57]
	v_pk_mul_f32 v[46:47], v[32:33], v[54:55]
	v_pk_mul_f32 v[48:49], v[34:35], v[56:57]
	v_pk_fma_f32 v[32:33], v[32:33], v[50:51], v[42:43] neg_lo:[0,0,1] neg_hi:[0,0,1]
	v_pk_fma_f32 v[34:35], v[34:35], v[52:53], v[44:45] neg_lo:[0,0,1] neg_hi:[0,0,1]
	v_pk_fma_f32 v[36:37], v[36:37], v[50:51], v[46:47]
	v_pk_fma_f32 v[38:39], v[38:39], v[52:53], v[48:49]
	v_pk_mul_f32 v[32:33], v[32:33], v[12:13] op_sel_hi:[1,0]
	v_pk_mul_f32 v[34:35], v[34:35], v[12:13] op_sel_hi:[1,0]
	v_pk_mul_f32 v[36:37], v[36:37], v[12:13] op_sel_hi:[1,0]
	v_pk_mul_f32 v[38:39], v[38:39], v[12:13] op_sel_hi:[1,0]
	v_cvt_pk_bf16_f32 v58, v32, v33
	v_cvt_pk_bf16_f32 v59, v34, v35
	v_cvt_pk_bf16_f32 v60, v36, v37
	v_cvt_pk_bf16_f32 v61, v38, v39
	global_store_dwordx2 v2, v[58:59], s[30:31] offset:1024
	global_store_dwordx2 v2, v[60:61], s[30:31] offset:1088
	s_waitcnt vmcnt(40)
; __device__ __forceinline__ bf16_t f2bf(float f) { return (bf16_t)(cvt_pk_bf16(f, 0.f) & 0xffffu); }
; __device__ __forceinline__ void prep_phase(const Ctx& X, const bf16_t* QKV, const float* qg, const float* kg, bf16_t* QP, bf16_t* KP, bf16_t* VT) {
;     ...
;             const float pos = (f < 16) ? (float)(t >> 6) : (float)(t & 63); const float ang = pos * invf; const float rev = __builtin_amdgcn_fractf(ang * 0.15915494309189535f); const float cs = __builtin_amdgcn_cosf(rev), sn = __builtin_amdgcn_sinf(rev);
;             if (lat) {
; #pragma unroll
;                 for (int h = 0; h < 8; ++h) { const float x = bf2f(rowp[h * 64 + X.lane]); const float y = x * rsqrtf(wave_sum(x * x) * (1.0f / 64.0f) + 1e-6f) * qgl; const float pr = __shfl_xor(y, 32);
;                     const float o = X.lane < 32 ? (y * cs - pr * sn) : (pr * sn + y * cs); QP[((size_t)R * 8 + h) * 64 + X.lane] = f2bf(o * (0.125f * LOG2E)); } }
	s_lshl_b32 s0, s12, 3
	s_add_u32 s0, s0, 6
	v_mov_b32_e32 v63, s0
	v_cndmask_b32_e64 v63, v63, v14, s[10:11]
	v_lshl_add_u32 v62, v63, 6, v9
	ds_read_b128 v[50:53], v62 offset:18432
	ds_read_b128 v[54:57], v62 offset:22528
	v_lshlrev_b32_e32 v32, 16, v136
	v_and_b32_e32 v33, 0xffff0000, v136
	v_lshlrev_b32_e32 v34, 16, v137
	v_and_b32_e32 v35, 0xffff0000, v137
	v_lshlrev_b32_e32 v36, 16, v138
	v_and_b32_e32 v37, 0xffff0000, v138
	v_lshlrev_b32_e32 v38, 16, v139
	v_and_b32_e32 v39, 0xffff0000, v139
	v_pk_mul_f32 v[40:41], v[32:33], v[32:33]
	v_pk_fma_f32 v[40:41], v[34:35], v[34:35], v[40:41]
	v_pk_fma_f32 v[40:41], v[36:37], v[36:37], v[40:41]
	v_pk_fma_f32 v[40:41], v[38:39], v[38:39], v[40:41]
	v_add_f32_e32 v40, v40, v41
	s_nop 1
	v_add_f32_dpp v40, v40, v40 quad_perm:[1,0,3,2] row_mask:0xf bank_mask:0xf
	s_nop 1
	v_add_f32_dpp v40, v40, v40 quad_perm:[2,3,0,1] row_mask:0xf bank_mask:0xf
	s_nop 1
	v_add_f32_dpp v40, v40, v40 row_half_mirror row_mask:0xf bank_mask:0xf
	s_nop 1
	v_fmamk_f32 v40, v40, 0x3c800000, v10
	v_rsq_f32_e32 v40, v40
	s_nop 0
	v_pk_mul_f32 v[32:33], v[32:33], v[40:41] op_sel_hi:[1,0]
	v_pk_mul_f32 v[34:35], v[34:35], v[40:41] op_sel_hi:[1,0]
	v_pk_mul_f32 v[36:37], v[36:37], v[40:41] op_sel_hi:[1,0]
	v_pk_mul_f32 v[38:39], v[38:39], v[40:41] op_sel_hi:[1,0]
	v_pk_mul_f32 v[32:33], v[32:33], v[16:17]
	v_pk_mul_f32 v[34:35], v[34:35], v[18:19]
	v_pk_mul_f32 v[36:37], v[36:37], v[20:21]
	v_pk_mul_f32 v[38:39], v[38:39], v[22:23]
	s_waitcnt lgkmcnt(0)
	v_pk_mul_f32 v[42:43], v[36:37], v[54:55]
	v_pk_mul_f32 v[44:45], v[38:39], v[56:57]
	v_pk_mul_f32 v[46:47], v[32:33], v[54:55]
	v_pk_mul_f32 v[48:49], v[34:35], v[56:57]
	v_pk_fma_f32 v[32:33], v[32:33], v[50:51], v[42:43] neg_lo:[0,0,1] neg_hi:[0,0,1]
	v_pk_fma_f32 v[34:35], v[34:35], v[52:53], v[44:45] neg_lo:[0,0,1] neg_hi:[0,0,1]
	v_pk_fma_f32 v[36:37], v[36:37], v[50:51], v[46:47]
	v_pk_fma_f32 v[38:39], v[38:39], v[52:53], v[48:49]
	v_pk_mul_f32 v[32:33], v[32:33], v[12:13] op_sel_hi:[1,0]
	v_pk_mul_f32 v[34:35], v[34:35], v[12:13] op_sel_hi:[1,0]
	v_pk_mul_f32 v[36:37], v[36:37], v[12:13] op_sel_hi:[1,0]
	v_pk_mul_f32 v[38:39], v[38:39], v[12:13] op_sel_hi:[1,0]
	v_cvt_pk_bf16_f32 v58, v32, v33
	v_cvt_pk_bf16_f32 v59, v34, v35
	v_cvt_pk_bf16_f32 v60, v36, v37
	v_cvt_pk_bf16_f32 v61, v38, v39
	global_store_dwordx2 v2, v[58:59], s[30:31] offset:2048
	global_store_dwordx2 v2, v[60:61], s[30:31] offset:2112
	s_waitcnt vmcnt(40)
	s_lshl_b32 s0, s12, 3
	s_add_u32 s0, s0, 7
	v_mov_b32_e32 v63, s0
	v_cndmask_b32_e64 v63, v63, v14, s[10:11]
	v_lshl_add_u32 v62, v63, 6, v9
	ds_read_b128 v[50:53], v62 offset:18432
	ds_read_b128 v[54:57], v62 offset:22528
	v_lshlrev_b32_e32 v32, 16, v140
	v_and_b32_e32 v33, 0xffff0000, v140
	v_lshlrev_b32_e32 v34, 16, v141
	v_and_b32_e32 v35, 0xffff0000, v141
	v_lshlrev_b32_e32 v36, 16, v142
	v_and_b32_e32 v37, 0xffff0000, v142
	v_lshlrev_b32_e32 v38, 16, v143
	v_and_b32_e32 v39, 0xffff0000, v143
	v_pk_mul_f32 v[40:41], v[32:33], v[32:33]
	v_pk_fma_f32 v[40:41], v[34:35], v[34:35], v[40:41]
	v_pk_fma_f32 v[40:41], v[36:37], v[36:37], v[40:41]
	v_pk_fma_f32 v[40:41], v[38:39], v[38:39], v[40:41]
	v_add_f32_e32 v40, v40, v41
	s_nop 1
	v_add_f32_dpp v40, v40, v40 quad_perm:[1,0,3,2] row_mask:0xf bank_mask:0xf
	s_nop 1
	v_add_f32_dpp v40, v40, v40 quad_perm:[2,3,0,1] row_mask:0xf bank_mask:0xf
	s_nop 1
	v_add_f32_dpp v40, v40, v40 row_half_mirror row_mask:0xf bank_mask:0xf
	s_nop 1
	v_fmamk_f32 v40, v40, 0x3c800000, v10
	v_rsq_f32_e32 v40, v40
	s_nop 0
	v_pk_mul_f32 v[32:33], v[32:33], v[40:41] op_sel_hi:[1,0]
	v_pk_mul_f32 v[34:35], v[34:35], v[40:41] op_sel_hi:[1,0]
	v_pk_mul_f32 v[36:37], v[36:37], v[40:41] op_sel_hi:[1,0]
	v_pk_mul_f32 v[38:39], v[38:39], v[40:41] op_sel_hi:[1,0]
	v_pk_mul_f32 v[32:33], v[32:33], v[16:17]
	v_pk_mul_f32 v[34:35], v[34:35], v[18:19]
	v_pk_mul_f32 v[36:37], v[36:37], v[20:21]
	v_pk_mul_f32 v[38:39], v[38:39], v[22:23]
	s_waitcnt lgkmcnt(0)
	v_pk_mul_f32 v[42:43], v[36:37], v[54:55]
	v_pk_mul_f32 v[44:45], v[38:39], v[56:57]
	v_pk_mul_f32 v[46:47], v[32:33], v[54:55]
	v_pk_mul_f32 v[48:49], v[34:35], v[56:57]
	v_pk_fma_f32 v[32:33], v[32:33], v[50:51], v[42:43] neg_lo:[0,0,1] neg_hi:[0,0,1]
	v_pk_fma_f32 v[34:35], v[34:35], v[52:53], v[44:45] neg_lo:[0,0,1] neg_hi:[0,0,1]
	v_pk_fma_f32 v[36:37], v[36:37], v[50:51], v[46:47]
	v_pk_fma_f32 v[38:39], v[38:39], v[52:53], v[48:49]
	v_pk_mul_f32 v[32:33], v[32:33], v[12:13] op_sel_hi:[1,0]
	v_pk_mul_f32 v[34:35], v[34:35], v[12:13] op_sel_hi:[1,0]
	v_pk_mul_f32 v[36:37], v[36:37], v[12:13] op_sel_hi:[1,0]
	v_pk_mul_f32 v[38:39], v[38:39], v[12:13] op_sel_hi:[1,0]
	v_cvt_pk_bf16_f32 v58, v32, v33
	v_cvt_pk_bf16_f32 v59, v34, v35
	v_cvt_pk_bf16_f32 v60, v36, v37
	v_cvt_pk_bf16_f32 v61, v38, v39
	global_store_dwordx2 v2, v[58:59], s[30:31] offset:3072
	global_store_dwordx2 v2, v[60:61], s[30:31] offset:3136
	s_waitcnt lgkmcnt(0)
	s_barrier
; __device__ __forceinline__ bf16_t f2bf(float f) { return (bf16_t)(cvt_pk_bf16(f, 0.f) & 0xffffu); }
; __device__ __forceinline__ void prep_phase(const Ctx& X, const bf16_t* QKV, const float* qg, const float* kg, bf16_t* QP, bf16_t* KP, bf16_t* VT) {
;     ...
; #pragma unroll
;             for (int h = 0; h < 2; ++h) { const float x = bf2f(rowp[512 + h * 64 + X.lane]); float y = x * rsqrtf(wave_sum(x * x) * (1.0f / 64.0f) + 1e-6f) * kgl;
;                 if (lat) { const float pr = __shfl_xor(y, 32); y = X.lane < 32 ? (y * cs - pr * sn) : (pr * sn + y * cs); }
;                 KP[((size_t)(b * 2 + h) * KPL + kp0 + tl) * 64 + X.lane] = f2bf(y);
;                 vt[(h * 64 + X.lane) * 72 + tl] = rowp[640 + h * 64 + X.lane]; }
;         }
;         __syncthreads();
;         { const int row = X.tid >> 2, ch = X.tid & 3, h = row >> 6, d = row & 63;
;             const u32x4 a = *(const u32x4*)(vt + row * 72 + ch * 16), c2 = *(const u32x4*)(vt + row * 72 + ch * 16 + 8);
;             bf16_t* dp = VT + ((size_t)(b * 2 + h) * 64 + d) * KPL + kp0 + ch * 16; *(u32x4*)dp = a; *(u32x4*)(dp + 8) = c2; }
	ds_read_b128 v[32:35], v7
	ds_read_b128 v[36:39], v7 offset:16
	s_waitcnt lgkmcnt(0)
	global_store_dwordx4 v8, v[32:35], s[38:39]
	global_store_dwordx4 v8, v[36:39], s[38:39] offset:16
	s_cmp_lt_u32 s2, 32
	s_cbranch_scc0 .LBB0_624
	s_sub_u32 s0, s28, 0x200
	s_lshr_b32 s33, s0, 2
	s_and_b32 s0, s0, 3
	s_lshl_b32 s34, s0, 6
	s_add_u32 s34, s34, 0x1000
	s_mul_i32 s0, s33, 0x110000
	s_lshl_b32 s1, s12, 3
	s_add_u32 s1, s1, s34
	s_lshl_b32 s1, s1, 7
	s_add_u32 s0, s0, s1
	s_add_u32 s36, s88, s0
	s_addc_u32 s37, s89, 0
	s_add_u32 s36, s36, 0x17400000
	s_addc_u32 s37, s37, 0
	s_mul_i32 s0, s33, 0x110000
	s_lshl_b32 s1, s34, 1
	s_add_u32 s0, s0, s1
	s_add_u32 s38, s88, s0
	s_addc_u32 s39, s89, 0
	s_add_u32 s38, s38, 0x17d00000
	s_addc_u32 s39, s39, 0
	s_barrier
	s_waitcnt vmcnt(26)
	ds_write_b16 v6, v104 offset:0
	ds_write_b16_d16_hi v6, v104 offset:144
	ds_write_b16 v6, v105 offset:288
	ds_write_b16_d16_hi v6, v105 offset:432
	ds_write_b16 v6, v106 offset:4
	ds_write_b16_d16_hi v6, v106 offset:148
	ds_write_b16 v6, v107 offset:292
	ds_write_b16_d16_hi v6, v107 offset:436
	ds_write_b16 v6, v108 offset:8
	ds_write_b16_d16_hi v6, v108 offset:152
	ds_write_b16 v6, v109 offset:296
	ds_write_b16_d16_hi v6, v109 offset:440
	ds_write_b16 v6, v110 offset:12
	ds_write_b16_d16_hi v6, v110 offset:156
	ds_write_b16 v6, v111 offset:300
	ds_write_b16_d16_hi v6, v111 offset:444
	s_waitcnt vmcnt(24)
	v_lshlrev_b32_e32 v32, 16, v96
	v_and_b32_e32 v33, 0xffff0000, v96
	v_lshlrev_b32_e32 v34, 16, v97
	v_and_b32_e32 v35, 0xffff0000, v97
	v_lshlrev_b32_e32 v36, 16, v98
	v_and_b32_e32 v37, 0xffff0000, v98
	v_lshlrev_b32_e32 v38, 16, v99
	v_and_b32_e32 v39, 0xffff0000, v99
	v_pk_mul_f32 v[40:41], v[32:33], v[32:33]
	v_pk_fma_f32 v[40:41], v[34:35], v[34:35], v[40:41]
	v_pk_fma_f32 v[40:41], v[36:37], v[36:37], v[40:41]
	v_pk_fma_f32 v[40:41], v[38:39], v[38:39], v[40:41]
	v_add_f32_e32 v40, v40, v41
	s_nop 1
	v_add_f32_dpp v40, v40, v40 quad_perm:[1,0,3,2] row_mask:0xf bank_mask:0xf
	s_nop 1
	v_add_f32_dpp v40, v40, v40 quad_perm:[2,3,0,1] row_mask:0xf bank_mask:0xf
	s_nop 1
	v_add_f32_dpp v40, v40, v40 row_half_mirror row_mask:0xf bank_mask:0xf
	s_nop 1
	v_fmamk_f32 v40, v40, 0x3c800000, v10
	v_rsq_f32_e32 v40, v40
	s_nop 0
	v_pk_mul_f32 v[32:33], v[32:33], v[40:41] op_sel_hi:[1,0]
	v_pk_mul_f32 v[34:35], v[34:35], v[40:41] op_sel_hi:[1,0]
	v_pk_mul_f32 v[36:37], v[36:37], v[40:41] op_sel_hi:[1,0]
	v_pk_mul_f32 v[38:39], v[38:39], v[40:41] op_sel_hi:[1,0]
	v_pk_mul_f32 v[32:33], v[32:33], v[24:25]
	v_pk_mul_f32 v[34:35], v[34:35], v[26:27]
	v_pk_mul_f32 v[36:37], v[36:37], v[28:29]
	v_pk_mul_f32 v[38:39], v[38:39], v[30:31]
	v_cvt_pk_bf16_f32 v58, v32, v33
	v_cvt_pk_bf16_f32 v59, v34, v35
	v_cvt_pk_bf16_f32 v60, v36, v37
	v_cvt_pk_bf16_f32 v61, v38, v39
	global_store_dwordx2 v4, v[58:59], s[36:37]
	global_store_dwordx2 v4, v[60:61], s[36:37] offset:64
	s_waitcnt vmcnt(24)
	v_lshlrev_b32_e32 v32, 16, v100
	v_and_b32_e32 v33, 0xffff0000, v100
	v_lshlrev_b32_e32 v34, 16, v101
	v_and_b32_e32 v35, 0xffff0000, v101
	v_lshlrev_b32_e32 v36, 16, v102
	v_and_b32_e32 v37, 0xffff0000, v102
	v_lshlrev_b32_e32 v38, 16, v103
	v_and_b32_e32 v39, 0xffff0000, v103
	v_pk_mul_f32 v[40:41], v[32:33], v[32:33]
	v_pk_fma_f32 v[40:41], v[34:35], v[34:35], v[40:41]
	v_pk_fma_f32 v[40:41], v[36:37], v[36:37], v[40:41]
	v_pk_fma_f32 v[40:41], v[38:39], v[38:39], v[40:41]
	v_add_f32_e32 v40, v40, v41
	s_nop 1
	v_add_f32_dpp v40, v40, v40 quad_perm:[1,0,3,2] row_mask:0xf bank_mask:0xf
	s_nop 1
	v_add_f32_dpp v40, v40, v40 quad_perm:[2,3,0,1] row_mask:0xf bank_mask:0xf
	s_nop 1
	v_add_f32_dpp v40, v40, v40 row_half_mirror row_mask:0xf bank_mask:0xf
	s_nop 1
	v_fmamk_f32 v40, v40, 0x3c800000, v10
	v_rsq_f32_e32 v40, v40
	s_nop 0
	v_pk_mul_f32 v[32:33], v[32:33], v[40:41] op_sel_hi:[1,0]
	v_pk_mul_f32 v[34:35], v[34:35], v[40:41] op_sel_hi:[1,0]
	v_pk_mul_f32 v[36:37], v[36:37], v[40:41] op_sel_hi:[1,0]
	v_pk_mul_f32 v[38:39], v[38:39], v[40:41] op_sel_hi:[1,0]
	v_pk_mul_f32 v[32:33], v[32:33], v[24:25]
	v_pk_mul_f32 v[34:35], v[34:35], v[26:27]
	v_pk_mul_f32 v[36:37], v[36:37], v[28:29]
	v_pk_mul_f32 v[38:39], v[38:39], v[30:31]
	v_cvt_pk_bf16_f32 v58, v32, v33
	v_cvt_pk_bf16_f32 v59, v34, v35
	v_cvt_pk_bf16_f32 v60, v36, v37
	v_cvt_pk_bf16_f32 v61, v38, v39
	global_store_dwordx2 v4, v[58:59], s[36:37] offset:512
	global_store_dwordx2 v4, v[60:61], s[36:37] offset:576
	s_waitcnt lgkmcnt(0)
	s_barrier
	ds_read_b128 v[32:35], v7
	ds_read_b128 v[36:39], v7 offset:16
	s_waitcnt lgkmcnt(0)
	global_store_dwordx4 v8, v[32:35], s[38:39]
	global_store_dwordx4 v8, v[36:39], s[38:39] offset:16
